# GEMM load segments: LDS-DMA stages issued before the ds_read fragment loads (v29 + dmafirst)
# baseline (speedup 1.0000x reference)
.LBB0_226:
	s_add_u32 s26, s24, 0xfff80080
	s_addc_u32 s27, s25, -1
	s_cmp_eq_u32 s60, 28
	s_cselect_b32 s29, s17, s27
	s_cselect_b32 s28, s54, s26
	s_cselect_b32 s27, s15, s59
	s_cselect_b32 s26, s55, s58
	v_lshl_add_u64 v[190:191], s[24:25], 0, v[136:137]
	s_add_i32 m0, s23, 0xc000
	s_nop 0
	global_load_lds_dwordx4 v[190:191], off
	v_lshl_add_u64 v[190:191], s[24:25], 0, v[138:139]
	s_add_i32 m0, s23, 0xe000
	s_nop 0
	global_load_lds_dwordx4 v[190:191], off
	ds_read_b128 v[144:147], v151
	ds_read_b128 v[154:157], v151 offset:1024
	ds_read_b128 v[158:161], v151 offset:2048
	ds_read_b128 v[162:165], v151 offset:3072
	ds_read_b128 v[166:169], v152
	ds_read_b128 v[170:173], v152 offset:1024
	ds_read_b128 v[174:177], v152 offset:2048
	ds_read_b128 v[178:181], v152 offset:3072
	ds_read_b128 v[182:185], v153
	ds_read_b128 v[186:189], v153 offset:1024
	ds_read_b128 v[194:197], v153 offset:2048
	ds_read_b128 v[198:201], v153 offset:3072
	ds_read_b128 v[202:205], v153 offset:4096
	ds_read_b128 v[206:209], v153 offset:5120
	ds_read_b128 v[210:213], v153 offset:6144
	ds_read_b128 v[214:217], v153 offset:7168
	s_waitcnt vmcnt(8)
	s_waitcnt lgkmcnt(0)
	s_barrier
	s_waitcnt lgkmcnt(0)
	v_mfma_f32_16x16x32_bf16 v[124:127], v[144:147], v[182:185], v[124:127]
	v_mfma_f32_16x16x32_bf16 v[120:123], v[158:161], v[182:185], v[120:123]
	v_mfma_f32_16x16x32_bf16 v[116:119], v[144:147], v[194:197], v[116:119]
	v_mfma_f32_16x16x32_bf16 v[108:111], v[158:161], v[194:197], v[108:111]
	v_mfma_f32_16x16x32_bf16 v[100:103], v[144:147], v[202:205], v[100:103]
	v_mfma_f32_16x16x32_bf16 v[92:95], v[158:161], v[202:205], v[92:95]
	v_mfma_f32_16x16x32_bf16 v[84:87], v[144:147], v[210:213], v[84:87]
	v_mfma_f32_16x16x32_bf16 v[76:79], v[158:161], v[210:213], v[76:79]
	v_mfma_f32_16x16x32_bf16 v[124:127], v[154:157], v[186:189], v[124:127]
	v_mfma_f32_16x16x32_bf16 v[120:123], v[162:165], v[186:189], v[120:123]
	v_mfma_f32_16x16x32_bf16 v[116:119], v[154:157], v[198:201], v[116:119]
	v_mfma_f32_16x16x32_bf16 v[108:111], v[162:165], v[198:201], v[108:111]
	v_mfma_f32_16x16x32_bf16 v[100:103], v[154:157], v[206:209], v[100:103]
	v_mfma_f32_16x16x32_bf16 v[92:95], v[162:165], v[206:209], v[92:95]
	v_mfma_f32_16x16x32_bf16 v[84:87], v[154:157], v[214:217], v[84:87]
	v_mfma_f32_16x16x32_bf16 v[76:79], v[162:165], v[214:217], v[76:79]
	v_mfma_f32_16x16x32_bf16 v[112:115], v[166:169], v[182:185], v[112:115]
	v_mfma_f32_16x16x32_bf16 v[104:107], v[174:177], v[182:185], v[104:107]
	v_mfma_f32_16x16x32_bf16 v[96:99], v[166:169], v[194:197], v[96:99]
	v_mfma_f32_16x16x32_bf16 v[88:91], v[174:177], v[194:197], v[88:91]
	v_mfma_f32_16x16x32_bf16 v[80:83], v[166:169], v[202:205], v[80:83]
	v_mfma_f32_16x16x32_bf16 v[72:75], v[174:177], v[202:205], v[72:75]
	v_mfma_f32_16x16x32_bf16 v[68:71], v[166:169], v[210:213], v[68:71]
	v_mfma_f32_16x16x32_bf16 v[64:67], v[174:177], v[210:213], v[64:67]
	v_mfma_f32_16x16x32_bf16 v[112:115], v[170:173], v[186:189], v[112:115]
	v_mfma_f32_16x16x32_bf16 v[104:107], v[178:181], v[186:189], v[104:107]
	v_mfma_f32_16x16x32_bf16 v[96:99], v[170:173], v[198:201], v[96:99]
	v_mfma_f32_16x16x32_bf16 v[88:91], v[178:181], v[198:201], v[88:91]
	v_mfma_f32_16x16x32_bf16 v[80:83], v[170:173], v[206:209], v[80:83]
	v_mfma_f32_16x16x32_bf16 v[72:75], v[178:181], v[206:209], v[72:75]
	v_mfma_f32_16x16x32_bf16 v[68:71], v[170:173], v[214:217], v[68:71]
	v_mfma_f32_16x16x32_bf16 v[64:67], v[178:181], v[214:217], v[64:67]
	s_barrier
	s_add_i32 s33, s48, s36
	v_lshl_add_u64 v[190:191], s[26:27], 0, v[132:133]
	s_mov_b32 m0, s33
	s_nop 0
	global_load_lds_dwordx4 v[190:191], off
	s_add_i32 m0, s33, 0x2000
	s_add_u32 s62, s26, 0x80000
	v_lshl_add_u64 v[218:219], s[26:27], 0, v[128:129]
	s_addc_u32 s63, s27, 0
	s_add_i32 s33, s49, s36
	global_load_lds_dwordx4 v[218:219], off
	v_lshl_add_u64 v[220:221], s[62:63], 0, v[132:133]
	s_mov_b32 m0, s33
	v_lshl_add_u64 v[222:223], s[28:29], 0, v[130:131]
	global_load_lds_dwordx4 v[220:221], off
	v_lshl_add_u64 v[220:221], s[62:63], 0, v[128:129]
	s_add_i32 m0, s33, 0x2000
	s_nop 0
	global_load_lds_dwordx4 v[220:221], off
	v_lshl_add_u64 v[220:221], s[28:29], 0, v[134:135]
	s_mov_b32 m0, s23
	s_nop 0
	global_load_lds_dwordx4 v[220:221], off
	s_mov_b32 m0, s38
	s_nop 0
	global_load_lds_dwordx4 v[222:223], off
	ds_read_b128 v[182:185], v153 offset:16384
	ds_read_b128 v[186:189], v153 offset:17408
	ds_read_b128 v[194:197], v153 offset:18432
	ds_read_b128 v[198:201], v153 offset:19456
	ds_read_b128 v[202:205], v153 offset:20480
	ds_read_b128 v[206:209], v153 offset:21504
	ds_read_b128 v[210:213], v153 offset:22528
	ds_read_b128 v[214:217], v153 offset:23552
	s_waitcnt vmcnt(8)
	s_waitcnt lgkmcnt(0)
	s_barrier
	s_waitcnt lgkmcnt(0)
	v_mfma_f32_16x16x32_bf16 v[60:63], v[144:147], v[182:185], v[60:63]
	v_mfma_f32_16x16x32_bf16 v[56:59], v[158:161], v[182:185], v[56:59]
	v_mfma_f32_16x16x32_bf16 v[52:55], v[144:147], v[194:197], v[52:55]
	v_mfma_f32_16x16x32_bf16 v[44:47], v[158:161], v[194:197], v[44:47]
	v_mfma_f32_16x16x32_bf16 v[36:39], v[144:147], v[202:205], v[36:39]
	v_mfma_f32_16x16x32_bf16 v[28:31], v[158:161], v[202:205], v[28:31]
	v_mfma_f32_16x16x32_bf16 v[20:23], v[144:147], v[210:213], v[20:23]
	v_mfma_f32_16x16x32_bf16 v[12:15], v[158:161], v[210:213], v[12:15]
	v_mfma_f32_16x16x32_bf16 v[60:63], v[154:157], v[186:189], v[60:63]
	v_mfma_f32_16x16x32_bf16 v[56:59], v[162:165], v[186:189], v[56:59]
	v_mfma_f32_16x16x32_bf16 v[52:55], v[154:157], v[198:201], v[52:55]
	v_mfma_f32_16x16x32_bf16 v[44:47], v[162:165], v[198:201], v[44:47]
	v_mfma_f32_16x16x32_bf16 v[36:39], v[154:157], v[206:209], v[36:39]
	v_mfma_f32_16x16x32_bf16 v[28:31], v[162:165], v[206:209], v[28:31]
	v_mfma_f32_16x16x32_bf16 v[20:23], v[154:157], v[214:217], v[20:23]
	v_mfma_f32_16x16x32_bf16 v[12:15], v[162:165], v[214:217], v[12:15]
	v_mfma_f32_16x16x32_bf16 v[48:51], v[166:169], v[182:185], v[48:51]
	v_mfma_f32_16x16x32_bf16 v[40:43], v[174:177], v[182:185], v[40:43]
	v_mfma_f32_16x16x32_bf16 v[32:35], v[166:169], v[194:197], v[32:35]
	v_mfma_f32_16x16x32_bf16 v[24:27], v[174:177], v[194:197], v[24:27]
	v_mfma_f32_16x16x32_bf16 v[16:19], v[166:169], v[202:205], v[16:19]
	v_mfma_f32_16x16x32_bf16 v[8:11], v[174:177], v[202:205], v[8:11]
	v_mfma_f32_16x16x32_bf16 v[4:7], v[166:169], v[210:213], v[4:7]
	v_mfma_f32_16x16x32_bf16 v[0:3], v[174:177], v[210:213], v[0:3]
	v_mfma_f32_16x16x32_bf16 v[48:51], v[170:173], v[186:189], v[48:51]
	v_mfma_f32_16x16x32_bf16 v[40:43], v[178:181], v[186:189], v[40:43]
	v_mfma_f32_16x16x32_bf16 v[32:35], v[170:173], v[198:201], v[32:35]
	v_mfma_f32_16x16x32_bf16 v[24:27], v[178:181], v[198:201], v[24:27]
	v_mfma_f32_16x16x32_bf16 v[16:19], v[170:173], v[206:209], v[16:19]
	v_mfma_f32_16x16x32_bf16 v[8:11], v[178:181], v[206:209], v[8:11]
	v_mfma_f32_16x16x32_bf16 v[4:7], v[170:173], v[214:217], v[4:7]
	v_mfma_f32_16x16x32_bf16 v[0:3], v[178:181], v[214:217], v[0:3]
	s_barrier
	s_add_i32 s33, 0, 0x18000
	s_add_i32 s56, 0, 0x1c000
	s_add_u32 s28, s28, 0x80000
	s_addc_u32 s29, s29, 0
	s_mov_b32 m0, s39
	v_lshl_add_u64 v[224:225], s[28:29], 0, v[134:135]
	global_load_lds_dwordx4 v[224:225], off
	v_lshl_add_u64 v[224:225], s[28:29], 0, v[130:131]
	s_mov_b32 m0, s40
	s_nop 0
	global_load_lds_dwordx4 v[224:225], off
	v_add_u32_e32 v162, s33, v149
	v_add_u32_e32 v178, s56, v149
	ds_read_b128 v[144:147], v162
	ds_read_b128 v[154:157], v162 offset:1024
	ds_read_b128 v[158:161], v162 offset:2048
	ds_read_b128 v[162:165], v162 offset:3072
	ds_read_b128 v[166:169], v178
	ds_read_b128 v[170:173], v178 offset:1024
	ds_read_b128 v[174:177], v178 offset:2048
	ds_read_b128 v[178:181], v178 offset:3072
	ds_read_b128 v[182:185], v153 offset:32768
	ds_read_b128 v[186:189], v153 offset:33792
	ds_read_b128 v[194:197], v153 offset:34816
	ds_read_b128 v[198:201], v153 offset:35840
	ds_read_b128 v[202:205], v153 offset:36864
	ds_read_b128 v[206:209], v153 offset:37888
	ds_read_b128 v[210:213], v153 offset:38912
	ds_read_b128 v[214:217], v153 offset:39936
	s_waitcnt vmcnt(8)
	s_waitcnt lgkmcnt(0)
	s_barrier
	s_waitcnt lgkmcnt(0)
	v_mfma_f32_16x16x32_bf16 v[124:127], v[144:147], v[182:185], v[124:127]
	v_mfma_f32_16x16x32_bf16 v[120:123], v[158:161], v[182:185], v[120:123]
	v_mfma_f32_16x16x32_bf16 v[116:119], v[144:147], v[194:197], v[116:119]
	v_mfma_f32_16x16x32_bf16 v[108:111], v[158:161], v[194:197], v[108:111]
	v_mfma_f32_16x16x32_bf16 v[100:103], v[144:147], v[202:205], v[100:103]
	v_mfma_f32_16x16x32_bf16 v[92:95], v[158:161], v[202:205], v[92:95]
	v_mfma_f32_16x16x32_bf16 v[84:87], v[144:147], v[210:213], v[84:87]
	v_mfma_f32_16x16x32_bf16 v[76:79], v[158:161], v[210:213], v[76:79]
	v_mfma_f32_16x16x32_bf16 v[124:127], v[154:157], v[186:189], v[124:127]
	v_mfma_f32_16x16x32_bf16 v[120:123], v[162:165], v[186:189], v[120:123]
	v_mfma_f32_16x16x32_bf16 v[116:119], v[154:157], v[198:201], v[116:119]
	v_mfma_f32_16x16x32_bf16 v[108:111], v[162:165], v[198:201], v[108:111]
	v_mfma_f32_16x16x32_bf16 v[100:103], v[154:157], v[206:209], v[100:103]
	v_mfma_f32_16x16x32_bf16 v[92:95], v[162:165], v[206:209], v[92:95]
	v_mfma_f32_16x16x32_bf16 v[84:87], v[154:157], v[214:217], v[84:87]
	v_mfma_f32_16x16x32_bf16 v[76:79], v[162:165], v[214:217], v[76:79]
	v_mfma_f32_16x16x32_bf16 v[112:115], v[166:169], v[182:185], v[112:115]
	v_mfma_f32_16x16x32_bf16 v[104:107], v[174:177], v[182:185], v[104:107]
	v_mfma_f32_16x16x32_bf16 v[96:99], v[166:169], v[194:197], v[96:99]
	v_mfma_f32_16x16x32_bf16 v[88:91], v[174:177], v[194:197], v[88:91]
	v_mfma_f32_16x16x32_bf16 v[80:83], v[166:169], v[202:205], v[80:83]
	v_mfma_f32_16x16x32_bf16 v[72:75], v[174:177], v[202:205], v[72:75]
	v_mfma_f32_16x16x32_bf16 v[68:71], v[166:169], v[210:213], v[68:71]
	v_mfma_f32_16x16x32_bf16 v[64:67], v[174:177], v[210:213], v[64:67]
	v_mfma_f32_16x16x32_bf16 v[112:115], v[170:173], v[186:189], v[112:115]
	v_mfma_f32_16x16x32_bf16 v[104:107], v[178:181], v[186:189], v[104:107]
	v_mfma_f32_16x16x32_bf16 v[96:99], v[170:173], v[198:201], v[96:99]
	v_mfma_f32_16x16x32_bf16 v[88:91], v[178:181], v[198:201], v[88:91]
	v_mfma_f32_16x16x32_bf16 v[80:83], v[170:173], v[206:209], v[80:83]
	v_mfma_f32_16x16x32_bf16 v[72:75], v[178:181], v[206:209], v[72:75]
	v_mfma_f32_16x16x32_bf16 v[68:71], v[170:173], v[214:217], v[68:71]
	v_mfma_f32_16x16x32_bf16 v[64:67], v[178:181], v[214:217], v[64:67]
	s_barrier
	s_add_i32 s28, s33, s36
	v_lshl_add_u64 v[190:191], v[190:191], 0, s[10:11]
	s_mov_b32 m0, s28
	s_nop 0
	global_load_lds_dwordx4 v[190:191], off
	s_add_i32 m0, s28, 0x2000
	s_add_u32 s26, s26, 0x80080
	v_lshl_add_u64 v[190:191], v[218:219], 0, s[10:11]
	s_addc_u32 s27, s27, 0
	s_add_i32 s28, s56, s36
	global_load_lds_dwordx4 v[190:191], off
	v_lshl_add_u64 v[190:191], s[26:27], 0, v[132:133]
	s_mov_b32 m0, s28
	s_nop 0
	global_load_lds_dwordx4 v[190:191], off
	v_lshl_add_u64 v[190:191], s[26:27], 0, v[128:129]
	s_add_i32 m0, s28, 0x2000
	s_nop 0
	global_load_lds_dwordx4 v[190:191], off
	v_lshl_add_u64 v[190:191], v[220:221], 0, s[10:11]
	s_mov_b32 m0, s42
	s_nop 0
	global_load_lds_dwordx4 v[190:191], off
	v_lshl_add_u64 v[190:191], v[222:223], 0, s[10:11]
	s_mov_b32 m0, s43
	s_nop 0
	global_load_lds_dwordx4 v[190:191], off
	ds_read_b128 v[182:185], v153 offset:49152
	ds_read_b128 v[186:189], v153 offset:50176
	ds_read_b128 v[194:197], v153 offset:51200
	ds_read_b128 v[198:201], v153 offset:52224
	ds_read_b128 v[202:205], v153 offset:53248
	ds_read_b128 v[206:209], v153 offset:54272
	ds_read_b128 v[210:213], v153 offset:55296
	ds_read_b128 v[214:217], v153 offset:56320
	s_waitcnt vmcnt(8)
	s_waitcnt lgkmcnt(0)
	s_barrier
	s_waitcnt lgkmcnt(0)
	v_mfma_f32_16x16x32_bf16 v[60:63], v[144:147], v[182:185], v[60:63]
	v_mfma_f32_16x16x32_bf16 v[56:59], v[158:161], v[182:185], v[56:59]
	v_mfma_f32_16x16x32_bf16 v[52:55], v[144:147], v[194:197], v[52:55]
	v_mfma_f32_16x16x32_bf16 v[44:47], v[158:161], v[194:197], v[44:47]
	v_mfma_f32_16x16x32_bf16 v[36:39], v[144:147], v[202:205], v[36:39]
	v_mfma_f32_16x16x32_bf16 v[28:31], v[158:161], v[202:205], v[28:31]
	v_mfma_f32_16x16x32_bf16 v[20:23], v[144:147], v[210:213], v[20:23]
	v_mfma_f32_16x16x32_bf16 v[12:15], v[158:161], v[210:213], v[12:15]
	v_mfma_f32_16x16x32_bf16 v[60:63], v[154:157], v[186:189], v[60:63]
	v_mfma_f32_16x16x32_bf16 v[56:59], v[162:165], v[186:189], v[56:59]
	v_mfma_f32_16x16x32_bf16 v[52:55], v[154:157], v[198:201], v[52:55]
	v_mfma_f32_16x16x32_bf16 v[44:47], v[162:165], v[198:201], v[44:47]
	v_mfma_f32_16x16x32_bf16 v[36:39], v[154:157], v[206:209], v[36:39]
	v_mfma_f32_16x16x32_bf16 v[28:31], v[162:165], v[206:209], v[28:31]
	v_mfma_f32_16x16x32_bf16 v[20:23], v[154:157], v[214:217], v[20:23]
	v_mfma_f32_16x16x32_bf16 v[12:15], v[162:165], v[214:217], v[12:15]
	v_mfma_f32_16x16x32_bf16 v[48:51], v[166:169], v[182:185], v[48:51]
	v_mfma_f32_16x16x32_bf16 v[40:43], v[174:177], v[182:185], v[40:43]
	v_mfma_f32_16x16x32_bf16 v[32:35], v[166:169], v[194:197], v[32:35]
	v_mfma_f32_16x16x32_bf16 v[24:27], v[174:177], v[194:197], v[24:27]
	v_mfma_f32_16x16x32_bf16 v[16:19], v[166:169], v[202:205], v[16:19]
	v_mfma_f32_16x16x32_bf16 v[8:11], v[174:177], v[202:205], v[8:11]
	v_mfma_f32_16x16x32_bf16 v[4:7], v[166:169], v[210:213], v[4:7]
	v_mfma_f32_16x16x32_bf16 v[0:3], v[174:177], v[210:213], v[0:3]
	v_mfma_f32_16x16x32_bf16 v[48:51], v[170:173], v[186:189], v[48:51]
	v_mfma_f32_16x16x32_bf16 v[40:43], v[178:181], v[186:189], v[40:43]
	v_mfma_f32_16x16x32_bf16 v[32:35], v[170:173], v[198:201], v[32:35]
	v_mfma_f32_16x16x32_bf16 v[24:27], v[178:181], v[198:201], v[24:27]
	v_mfma_f32_16x16x32_bf16 v[16:19], v[170:173], v[206:209], v[16:19]
	v_mfma_f32_16x16x32_bf16 v[8:11], v[178:181], v[206:209], v[8:11]
	v_mfma_f32_16x16x32_bf16 v[4:7], v[170:173], v[214:217], v[4:7]
	v_mfma_f32_16x16x32_bf16 v[0:3], v[178:181], v[214:217], v[0:3]
	s_barrier
	s_add_i32 s60, s60, 2
	s_add_u32 s24, s24, 0x100
	s_addc_u32 s25, s25, 0
	s_add_u32 s58, s58, 0x100
	s_addc_u32 s59, s59, 0
	s_cmp_gt_u32 s60, 29
	s_cbranch_scc0 .LBB0_226
	s_and_b64 vcc, exec, s[12:13]
	s_cbranch_vccz .LBB0_229
	s_barrier

.LBB0_589:
	s_add_u32 s33, s48, 0xfff80080
	s_addc_u32 s50, s49, -1
	s_cmp_eq_u32 s77, 28
	s_cselect_b32 s59, s35, s50
	s_cselect_b32 s58, s41, s33
	s_cselect_b32 s51, s31, s75
	s_cselect_b32 s50, s73, s74
	v_lshl_add_u64 v[148:149], s[48:49], 0, v[136:137]
	s_add_i32 m0, s43, 0xc000
	s_nop 0
	global_load_lds_dwordx4 v[148:149], off
	v_lshl_add_u64 v[148:149], s[48:49], 0, v[138:139]
	s_add_i32 m0, s43, 0xe000
	s_nop 0
	global_load_lds_dwordx4 v[148:149], off
	ds_read_b128 v[144:147], v153
	ds_read_b128 v[158:161], v153 offset:1024
	ds_read_b128 v[162:165], v153 offset:2048
	ds_read_b128 v[166:169], v153 offset:3072
	ds_read_b128 v[170:173], v154
	ds_read_b128 v[174:177], v154 offset:1024
	ds_read_b128 v[178:181], v154 offset:2048
	ds_read_b128 v[182:185], v154 offset:3072
	ds_read_b128 v[186:189], v155
	ds_read_b128 v[194:197], v155 offset:1024
	ds_read_b128 v[198:201], v155 offset:2048
	ds_read_b128 v[202:205], v155 offset:3072
	ds_read_b128 v[206:209], v155 offset:4096
	ds_read_b128 v[210:213], v155 offset:5120
	ds_read_b128 v[214:217], v155 offset:6144
	ds_read_b128 v[218:221], v155 offset:7168
	s_waitcnt vmcnt(8)
	s_waitcnt lgkmcnt(0)
	s_barrier
	s_waitcnt lgkmcnt(0)
	v_mfma_f32_16x16x32_bf16 v[124:127], v[144:147], v[186:189], v[124:127]
	v_mfma_f32_16x16x32_bf16 v[120:123], v[162:165], v[186:189], v[120:123]
	v_mfma_f32_16x16x32_bf16 v[108:111], v[144:147], v[198:201], v[108:111]
	v_mfma_f32_16x16x32_bf16 v[104:107], v[162:165], v[198:201], v[104:107]
	v_mfma_f32_16x16x32_bf16 v[92:95], v[144:147], v[206:209], v[92:95]
	v_mfma_f32_16x16x32_bf16 v[88:91], v[162:165], v[206:209], v[88:91]
	v_mfma_f32_16x16x32_bf16 v[76:79], v[144:147], v[214:217], v[76:79]
	v_mfma_f32_16x16x32_bf16 v[72:75], v[162:165], v[214:217], v[72:75]
	v_mfma_f32_16x16x32_bf16 v[124:127], v[158:161], v[194:197], v[124:127]
	v_mfma_f32_16x16x32_bf16 v[120:123], v[166:169], v[194:197], v[120:123]
	v_mfma_f32_16x16x32_bf16 v[108:111], v[158:161], v[202:205], v[108:111]
	v_mfma_f32_16x16x32_bf16 v[104:107], v[166:169], v[202:205], v[104:107]
	v_mfma_f32_16x16x32_bf16 v[92:95], v[158:161], v[210:213], v[92:95]
	v_mfma_f32_16x16x32_bf16 v[88:91], v[166:169], v[210:213], v[88:91]
	v_mfma_f32_16x16x32_bf16 v[76:79], v[158:161], v[218:221], v[76:79]
	v_mfma_f32_16x16x32_bf16 v[72:75], v[166:169], v[218:221], v[72:75]
	v_mfma_f32_16x16x32_bf16 v[116:119], v[170:173], v[186:189], v[116:119]
	v_mfma_f32_16x16x32_bf16 v[112:115], v[178:181], v[186:189], v[112:115]
	v_mfma_f32_16x16x32_bf16 v[100:103], v[170:173], v[198:201], v[100:103]
	v_mfma_f32_16x16x32_bf16 v[96:99], v[178:181], v[198:201], v[96:99]
	v_mfma_f32_16x16x32_bf16 v[84:87], v[170:173], v[206:209], v[84:87]
	v_mfma_f32_16x16x32_bf16 v[80:83], v[178:181], v[206:209], v[80:83]
	v_mfma_f32_16x16x32_bf16 v[68:71], v[170:173], v[214:217], v[68:71]
	v_mfma_f32_16x16x32_bf16 v[64:67], v[178:181], v[214:217], v[64:67]
	v_mfma_f32_16x16x32_bf16 v[116:119], v[174:177], v[194:197], v[116:119]
	v_mfma_f32_16x16x32_bf16 v[112:115], v[182:185], v[194:197], v[112:115]
	v_mfma_f32_16x16x32_bf16 v[100:103], v[174:177], v[202:205], v[100:103]
	v_mfma_f32_16x16x32_bf16 v[96:99], v[182:185], v[202:205], v[96:99]
	v_mfma_f32_16x16x32_bf16 v[84:87], v[174:177], v[210:213], v[84:87]
	v_mfma_f32_16x16x32_bf16 v[80:83], v[182:185], v[210:213], v[80:83]
	v_mfma_f32_16x16x32_bf16 v[68:71], v[174:177], v[218:221], v[68:71]
	v_mfma_f32_16x16x32_bf16 v[64:67], v[182:185], v[218:221], v[64:67]
	s_barrier
	s_add_i32 s33, s71, s64
	v_lshl_add_u64 v[148:149], s[50:51], 0, v[130:131]
	s_mov_b32 m0, s33
	s_nop 0
	global_load_lds_dwordx4 v[148:149], off
	s_add_i32 m0, s33, 0x2000
	s_add_u32 s54, s50, 0x80000
	v_lshl_add_u64 v[190:191], s[50:51], 0, v[134:135]
	s_addc_u32 s55, s51, 0
	s_add_i32 s33, s72, s64
	global_load_lds_dwordx4 v[190:191], off
	v_lshl_add_u64 v[222:223], s[54:55], 0, v[130:131]
	s_mov_b32 m0, s33
	v_lshl_add_u64 v[224:225], s[58:59], 0, v[132:133]
	global_load_lds_dwordx4 v[222:223], off
	v_lshl_add_u64 v[222:223], s[54:55], 0, v[134:135]
	s_add_i32 m0, s33, 0x2000
	s_nop 0
	global_load_lds_dwordx4 v[222:223], off
	v_lshl_add_u64 v[222:223], s[58:59], 0, v[128:129]
	s_mov_b32 m0, s43
	s_nop 0
	global_load_lds_dwordx4 v[222:223], off
	s_mov_b32 m0, s65
	s_nop 0
	global_load_lds_dwordx4 v[224:225], off
	ds_read_b128 v[186:189], v155 offset:16384
	ds_read_b128 v[194:197], v155 offset:17408
	ds_read_b128 v[198:201], v155 offset:18432
	ds_read_b128 v[202:205], v155 offset:19456
	ds_read_b128 v[206:209], v155 offset:20480
	ds_read_b128 v[210:213], v155 offset:21504
	ds_read_b128 v[214:217], v155 offset:22528
	ds_read_b128 v[218:221], v155 offset:23552
	s_waitcnt vmcnt(8)
	s_waitcnt lgkmcnt(0)
	s_barrier
	s_waitcnt lgkmcnt(0)
	v_mfma_f32_16x16x32_bf16 v[60:63], v[144:147], v[186:189], v[60:63]
	v_mfma_f32_16x16x32_bf16 v[56:59], v[162:165], v[186:189], v[56:59]
	v_mfma_f32_16x16x32_bf16 v[44:47], v[144:147], v[198:201], v[44:47]
	v_mfma_f32_16x16x32_bf16 v[40:43], v[162:165], v[198:201], v[40:43]
	v_mfma_f32_16x16x32_bf16 v[28:31], v[144:147], v[206:209], v[28:31]
	v_mfma_f32_16x16x32_bf16 v[24:27], v[162:165], v[206:209], v[24:27]
	v_mfma_f32_16x16x32_bf16 v[12:15], v[144:147], v[214:217], v[12:15]
	v_mfma_f32_16x16x32_bf16 v[8:11], v[162:165], v[214:217], v[8:11]
	v_mfma_f32_16x16x32_bf16 v[60:63], v[158:161], v[194:197], v[60:63]
	v_mfma_f32_16x16x32_bf16 v[56:59], v[166:169], v[194:197], v[56:59]
	v_mfma_f32_16x16x32_bf16 v[44:47], v[158:161], v[202:205], v[44:47]
	v_mfma_f32_16x16x32_bf16 v[40:43], v[166:169], v[202:205], v[40:43]
	v_mfma_f32_16x16x32_bf16 v[28:31], v[158:161], v[210:213], v[28:31]
	v_mfma_f32_16x16x32_bf16 v[24:27], v[166:169], v[210:213], v[24:27]
	v_mfma_f32_16x16x32_bf16 v[12:15], v[158:161], v[218:221], v[12:15]
	v_mfma_f32_16x16x32_bf16 v[8:11], v[166:169], v[218:221], v[8:11]
	v_mfma_f32_16x16x32_bf16 v[52:55], v[170:173], v[186:189], v[52:55]
	v_mfma_f32_16x16x32_bf16 v[48:51], v[178:181], v[186:189], v[48:51]
	v_mfma_f32_16x16x32_bf16 v[36:39], v[170:173], v[198:201], v[36:39]
	v_mfma_f32_16x16x32_bf16 v[32:35], v[178:181], v[198:201], v[32:35]
	v_mfma_f32_16x16x32_bf16 v[20:23], v[170:173], v[206:209], v[20:23]
	v_mfma_f32_16x16x32_bf16 v[16:19], v[178:181], v[206:209], v[16:19]
	v_mfma_f32_16x16x32_bf16 v[4:7], v[170:173], v[214:217], v[4:7]
	v_mfma_f32_16x16x32_bf16 v[0:3], v[178:181], v[214:217], v[0:3]
	v_mfma_f32_16x16x32_bf16 v[52:55], v[174:177], v[194:197], v[52:55]
	v_mfma_f32_16x16x32_bf16 v[48:51], v[182:185], v[194:197], v[48:51]
	v_mfma_f32_16x16x32_bf16 v[36:39], v[174:177], v[202:205], v[36:39]
	v_mfma_f32_16x16x32_bf16 v[32:35], v[182:185], v[202:205], v[32:35]
	v_mfma_f32_16x16x32_bf16 v[20:23], v[174:177], v[210:213], v[20:23]
	v_mfma_f32_16x16x32_bf16 v[16:19], v[182:185], v[210:213], v[16:19]
	v_mfma_f32_16x16x32_bf16 v[4:7], v[174:177], v[218:221], v[4:7]
	v_mfma_f32_16x16x32_bf16 v[0:3], v[182:185], v[218:221], v[0:3]
	s_barrier
	s_add_i32 s33, 0, 0x18000
	s_add_i32 s56, 0, 0x1c000
	s_add_u32 s54, s58, 0x80000
	s_addc_u32 s55, s59, 0
	s_mov_b32 m0, s66
	v_lshl_add_u64 v[226:227], s[54:55], 0, v[128:129]
	global_load_lds_dwordx4 v[226:227], off
	v_lshl_add_u64 v[226:227], s[54:55], 0, v[132:133]
	s_mov_b32 m0, s67
	s_nop 0
	global_load_lds_dwordx4 v[226:227], off
	v_add_u32_e32 v157, s33, v151
	ds_read_b128 v[144:147], v157
	ds_read_b128 v[158:161], v157 offset:1024
	ds_read_b128 v[162:165], v157 offset:2048
	ds_read_b128 v[166:169], v157 offset:3072
	v_add_u32_e32 v157, s56, v151
	ds_read_b128 v[170:173], v157
	ds_read_b128 v[174:177], v157 offset:1024
	ds_read_b128 v[178:181], v157 offset:2048
	ds_read_b128 v[182:185], v157 offset:3072
	ds_read_b128 v[186:189], v155 offset:32768
	ds_read_b128 v[194:197], v155 offset:33792
	ds_read_b128 v[198:201], v155 offset:34816
	ds_read_b128 v[202:205], v155 offset:35840
	ds_read_b128 v[206:209], v155 offset:36864
	ds_read_b128 v[210:213], v155 offset:37888
	ds_read_b128 v[214:217], v155 offset:38912
	ds_read_b128 v[218:221], v155 offset:39936
	s_waitcnt vmcnt(8)
	s_waitcnt lgkmcnt(0)
	s_barrier
	s_waitcnt lgkmcnt(0)
	v_mfma_f32_16x16x32_bf16 v[124:127], v[144:147], v[186:189], v[124:127]
	v_mfma_f32_16x16x32_bf16 v[120:123], v[162:165], v[186:189], v[120:123]
	v_mfma_f32_16x16x32_bf16 v[108:111], v[144:147], v[198:201], v[108:111]
	v_mfma_f32_16x16x32_bf16 v[104:107], v[162:165], v[198:201], v[104:107]
	v_mfma_f32_16x16x32_bf16 v[92:95], v[144:147], v[206:209], v[92:95]
	v_mfma_f32_16x16x32_bf16 v[88:91], v[162:165], v[206:209], v[88:91]
	v_mfma_f32_16x16x32_bf16 v[76:79], v[144:147], v[214:217], v[76:79]
	v_mfma_f32_16x16x32_bf16 v[72:75], v[162:165], v[214:217], v[72:75]
	v_mfma_f32_16x16x32_bf16 v[124:127], v[158:161], v[194:197], v[124:127]
	v_mfma_f32_16x16x32_bf16 v[120:123], v[166:169], v[194:197], v[120:123]
	v_mfma_f32_16x16x32_bf16 v[108:111], v[158:161], v[202:205], v[108:111]
	v_mfma_f32_16x16x32_bf16 v[104:107], v[166:169], v[202:205], v[104:107]
	v_mfma_f32_16x16x32_bf16 v[92:95], v[158:161], v[210:213], v[92:95]
	v_mfma_f32_16x16x32_bf16 v[88:91], v[166:169], v[210:213], v[88:91]
	v_mfma_f32_16x16x32_bf16 v[76:79], v[158:161], v[218:221], v[76:79]
	v_mfma_f32_16x16x32_bf16 v[72:75], v[166:169], v[218:221], v[72:75]
	v_mfma_f32_16x16x32_bf16 v[116:119], v[170:173], v[186:189], v[116:119]
	v_mfma_f32_16x16x32_bf16 v[112:115], v[178:181], v[186:189], v[112:115]
	v_mfma_f32_16x16x32_bf16 v[100:103], v[170:173], v[198:201], v[100:103]
	v_mfma_f32_16x16x32_bf16 v[96:99], v[178:181], v[198:201], v[96:99]
	v_mfma_f32_16x16x32_bf16 v[84:87], v[170:173], v[206:209], v[84:87]
	v_mfma_f32_16x16x32_bf16 v[80:83], v[178:181], v[206:209], v[80:83]
	v_mfma_f32_16x16x32_bf16 v[68:71], v[170:173], v[214:217], v[68:71]
	v_mfma_f32_16x16x32_bf16 v[64:67], v[178:181], v[214:217], v[64:67]
	v_mfma_f32_16x16x32_bf16 v[116:119], v[174:177], v[194:197], v[116:119]
	v_mfma_f32_16x16x32_bf16 v[112:115], v[182:185], v[194:197], v[112:115]
	v_mfma_f32_16x16x32_bf16 v[100:103], v[174:177], v[202:205], v[100:103]
	v_mfma_f32_16x16x32_bf16 v[96:99], v[182:185], v[202:205], v[96:99]
	v_mfma_f32_16x16x32_bf16 v[84:87], v[174:177], v[210:213], v[84:87]
	v_mfma_f32_16x16x32_bf16 v[80:83], v[182:185], v[210:213], v[80:83]
	v_mfma_f32_16x16x32_bf16 v[68:71], v[174:177], v[218:221], v[68:71]
	v_mfma_f32_16x16x32_bf16 v[64:67], v[182:185], v[218:221], v[64:67]
	s_barrier
	s_add_i32 s33, s33, s64
	v_lshl_add_u64 v[148:149], v[148:149], 0, s[18:19]
	s_mov_b32 m0, s33
	s_nop 0
	global_load_lds_dwordx4 v[148:149], off
	s_add_i32 m0, s33, 0x2000
	s_add_u32 s50, s50, 0x80080
	v_lshl_add_u64 v[148:149], v[190:191], 0, s[18:19]
	s_addc_u32 s51, s51, 0
	s_add_i32 s33, s56, s64
	global_load_lds_dwordx4 v[148:149], off
	v_lshl_add_u64 v[148:149], s[50:51], 0, v[130:131]
	s_mov_b32 m0, s33
	s_nop 0
	global_load_lds_dwordx4 v[148:149], off
	v_lshl_add_u64 v[148:149], s[50:51], 0, v[134:135]
	s_add_i32 m0, s33, 0x2000
	s_nop 0
	global_load_lds_dwordx4 v[148:149], off
	v_lshl_add_u64 v[148:149], v[222:223], 0, s[18:19]
	s_mov_b32 m0, s69
	s_nop 0
	global_load_lds_dwordx4 v[148:149], off
	v_lshl_add_u64 v[148:149], v[224:225], 0, s[18:19]
	s_mov_b32 m0, s70
	s_nop 0
	global_load_lds_dwordx4 v[148:149], off
	ds_read_b128 v[186:189], v155 offset:49152
	ds_read_b128 v[194:197], v155 offset:50176
	ds_read_b128 v[198:201], v155 offset:51200
	ds_read_b128 v[202:205], v155 offset:52224
	ds_read_b128 v[206:209], v155 offset:53248
	ds_read_b128 v[210:213], v155 offset:54272
	ds_read_b128 v[214:217], v155 offset:55296
	ds_read_b128 v[218:221], v155 offset:56320
	s_waitcnt vmcnt(8)
	s_waitcnt lgkmcnt(0)
	s_barrier
	s_waitcnt lgkmcnt(0)
	v_mfma_f32_16x16x32_bf16 v[60:63], v[144:147], v[186:189], v[60:63]
	v_mfma_f32_16x16x32_bf16 v[56:59], v[162:165], v[186:189], v[56:59]
	v_mfma_f32_16x16x32_bf16 v[44:47], v[144:147], v[198:201], v[44:47]
	v_mfma_f32_16x16x32_bf16 v[40:43], v[162:165], v[198:201], v[40:43]
	v_mfma_f32_16x16x32_bf16 v[28:31], v[144:147], v[206:209], v[28:31]
	v_mfma_f32_16x16x32_bf16 v[24:27], v[162:165], v[206:209], v[24:27]
	v_mfma_f32_16x16x32_bf16 v[12:15], v[144:147], v[214:217], v[12:15]
	v_mfma_f32_16x16x32_bf16 v[8:11], v[162:165], v[214:217], v[8:11]
	v_mfma_f32_16x16x32_bf16 v[60:63], v[158:161], v[194:197], v[60:63]
	v_mfma_f32_16x16x32_bf16 v[56:59], v[166:169], v[194:197], v[56:59]
	v_mfma_f32_16x16x32_bf16 v[44:47], v[158:161], v[202:205], v[44:47]
	v_mfma_f32_16x16x32_bf16 v[40:43], v[166:169], v[202:205], v[40:43]
	v_mfma_f32_16x16x32_bf16 v[28:31], v[158:161], v[210:213], v[28:31]
	v_mfma_f32_16x16x32_bf16 v[24:27], v[166:169], v[210:213], v[24:27]
	v_mfma_f32_16x16x32_bf16 v[12:15], v[158:161], v[218:221], v[12:15]
	v_mfma_f32_16x16x32_bf16 v[8:11], v[166:169], v[218:221], v[8:11]
	v_mfma_f32_16x16x32_bf16 v[52:55], v[170:173], v[186:189], v[52:55]
	v_mfma_f32_16x16x32_bf16 v[48:51], v[178:181], v[186:189], v[48:51]
	v_mfma_f32_16x16x32_bf16 v[36:39], v[170:173], v[198:201], v[36:39]
	v_mfma_f32_16x16x32_bf16 v[32:35], v[178:181], v[198:201], v[32:35]
	v_mfma_f32_16x16x32_bf16 v[20:23], v[170:173], v[206:209], v[20:23]
	v_mfma_f32_16x16x32_bf16 v[16:19], v[178:181], v[206:209], v[16:19]
	v_mfma_f32_16x16x32_bf16 v[4:7], v[170:173], v[214:217], v[4:7]
	v_mfma_f32_16x16x32_bf16 v[0:3], v[178:181], v[214:217], v[0:3]
	v_mfma_f32_16x16x32_bf16 v[52:55], v[174:177], v[194:197], v[52:55]
	v_mfma_f32_16x16x32_bf16 v[48:51], v[182:185], v[194:197], v[48:51]
	v_mfma_f32_16x16x32_bf16 v[36:39], v[174:177], v[202:205], v[36:39]
	v_mfma_f32_16x16x32_bf16 v[32:35], v[182:185], v[202:205], v[32:35]
	v_mfma_f32_16x16x32_bf16 v[20:23], v[174:177], v[210:213], v[20:23]
	v_mfma_f32_16x16x32_bf16 v[16:19], v[182:185], v[210:213], v[16:19]
	v_mfma_f32_16x16x32_bf16 v[4:7], v[174:177], v[218:221], v[4:7]
	v_mfma_f32_16x16x32_bf16 v[0:3], v[182:185], v[218:221], v[0:3]
	s_barrier
	s_add_i32 s77, s77, 2
	s_add_u32 s48, s48, 0x100
	s_addc_u32 s49, s49, 0
	s_add_u32 s74, s74, 0x100
	s_addc_u32 s75, s75, 0
	s_cmp_gt_u32 s77, 29
	s_cbranch_scc0 .LBB0_589
	s_and_b64 vcc, exec, s[20:21]
	s_cbranch_vccz .LBB0_592
	s_barrier

.LBB0_673:
	s_add_u32 s33, s30, 0xfff80080
	s_addc_u32 s34, s31, -1
	s_cmp_eq_u32 s69, 28
	s_cselect_b32 s37, s25, s34
	s_cselect_b32 s36, s65, s33
	s_cselect_b32 s35, s23, s68
	s_cselect_b32 s34, s66, s67
	v_lshl_add_u64 v[148:149], s[30:31], 0, v[136:137]
	s_add_i32 m0, s48, 0xc000
	s_nop 0
	global_load_lds_dwordx4 v[148:149], off
	v_lshl_add_u64 v[148:149], s[30:31], 0, v[138:139]
	s_add_i32 m0, s48, 0xe000
	s_nop 0
	global_load_lds_dwordx4 v[148:149], off
	ds_read_b128 v[144:147], v153
	ds_read_b128 v[158:161], v153 offset:1024
	ds_read_b128 v[162:165], v153 offset:2048
	ds_read_b128 v[166:169], v153 offset:3072
	ds_read_b128 v[170:173], v154
	ds_read_b128 v[174:177], v154 offset:1024
	ds_read_b128 v[178:181], v154 offset:2048
	ds_read_b128 v[182:185], v154 offset:3072
	ds_read_b128 v[186:189], v155
	ds_read_b128 v[194:197], v155 offset:1024
	ds_read_b128 v[198:201], v155 offset:2048
	ds_read_b128 v[202:205], v155 offset:3072
	ds_read_b128 v[206:209], v155 offset:4096
	ds_read_b128 v[210:213], v155 offset:5120
	ds_read_b128 v[214:217], v155 offset:6144
	ds_read_b128 v[218:221], v155 offset:7168
	s_waitcnt vmcnt(8)
	s_waitcnt lgkmcnt(0)
	s_barrier
	s_waitcnt lgkmcnt(0)
	v_mfma_f32_16x16x32_bf16 v[116:119], v[144:147], v[186:189], v[116:119]
	v_mfma_f32_16x16x32_bf16 v[112:115], v[162:165], v[186:189], v[112:115]
	v_mfma_f32_16x16x32_bf16 v[100:103], v[144:147], v[198:201], v[100:103]
	v_mfma_f32_16x16x32_bf16 v[96:99], v[162:165], v[198:201], v[96:99]
	v_mfma_f32_16x16x32_bf16 v[84:87], v[144:147], v[206:209], v[84:87]
	v_mfma_f32_16x16x32_bf16 v[80:83], v[162:165], v[206:209], v[80:83]
	v_mfma_f32_16x16x32_bf16 v[68:71], v[144:147], v[214:217], v[68:71]
	v_mfma_f32_16x16x32_bf16 v[64:67], v[162:165], v[214:217], v[64:67]
	v_mfma_f32_16x16x32_bf16 v[116:119], v[158:161], v[194:197], v[116:119]
	v_mfma_f32_16x16x32_bf16 v[112:115], v[166:169], v[194:197], v[112:115]
	v_mfma_f32_16x16x32_bf16 v[100:103], v[158:161], v[202:205], v[100:103]
	v_mfma_f32_16x16x32_bf16 v[96:99], v[166:169], v[202:205], v[96:99]
	v_mfma_f32_16x16x32_bf16 v[84:87], v[158:161], v[210:213], v[84:87]
	v_mfma_f32_16x16x32_bf16 v[80:83], v[166:169], v[210:213], v[80:83]
	v_mfma_f32_16x16x32_bf16 v[68:71], v[158:161], v[218:221], v[68:71]
	v_mfma_f32_16x16x32_bf16 v[64:67], v[166:169], v[218:221], v[64:67]
	v_mfma_f32_16x16x32_bf16 v[124:127], v[170:173], v[186:189], v[124:127]
	v_mfma_f32_16x16x32_bf16 v[120:123], v[178:181], v[186:189], v[120:123]
	v_mfma_f32_16x16x32_bf16 v[108:111], v[170:173], v[198:201], v[108:111]
	v_mfma_f32_16x16x32_bf16 v[104:107], v[178:181], v[198:201], v[104:107]
	v_mfma_f32_16x16x32_bf16 v[92:95], v[170:173], v[206:209], v[92:95]
	v_mfma_f32_16x16x32_bf16 v[88:91], v[178:181], v[206:209], v[88:91]
	v_mfma_f32_16x16x32_bf16 v[76:79], v[170:173], v[214:217], v[76:79]
	v_mfma_f32_16x16x32_bf16 v[72:75], v[178:181], v[214:217], v[72:75]
	v_mfma_f32_16x16x32_bf16 v[124:127], v[174:177], v[194:197], v[124:127]
	v_mfma_f32_16x16x32_bf16 v[120:123], v[182:185], v[194:197], v[120:123]
	v_mfma_f32_16x16x32_bf16 v[108:111], v[174:177], v[202:205], v[108:111]
	v_mfma_f32_16x16x32_bf16 v[104:107], v[182:185], v[202:205], v[104:107]
	v_mfma_f32_16x16x32_bf16 v[92:95], v[174:177], v[210:213], v[92:95]
	v_mfma_f32_16x16x32_bf16 v[88:91], v[182:185], v[210:213], v[88:91]
	v_mfma_f32_16x16x32_bf16 v[76:79], v[174:177], v[218:221], v[76:79]
	v_mfma_f32_16x16x32_bf16 v[72:75], v[182:185], v[218:221], v[72:75]
	s_barrier
	s_add_i32 s33, s61, s42
	v_lshl_add_u64 v[148:149], s[34:35], 0, v[132:133]
	s_mov_b32 m0, s33
	s_nop 0
	global_load_lds_dwordx4 v[148:149], off
	s_add_i32 m0, s33, 0x2000
	s_add_u32 s54, s34, 0x80000
	v_lshl_add_u64 v[190:191], s[34:35], 0, v[128:129]
	s_addc_u32 s55, s35, 0
	s_add_i32 s33, s62, s42
	global_load_lds_dwordx4 v[190:191], off
	v_lshl_add_u64 v[222:223], s[54:55], 0, v[132:133]
	s_mov_b32 m0, s33
	v_lshl_add_u64 v[224:225], s[36:37], 0, v[130:131]
	global_load_lds_dwordx4 v[222:223], off
	v_lshl_add_u64 v[222:223], s[54:55], 0, v[128:129]
	s_add_i32 m0, s33, 0x2000
	s_nop 0
	global_load_lds_dwordx4 v[222:223], off
	v_lshl_add_u64 v[222:223], s[36:37], 0, v[134:135]
	s_mov_b32 m0, s48
	s_nop 0
	global_load_lds_dwordx4 v[222:223], off
	s_mov_b32 m0, s49
	s_nop 0
	global_load_lds_dwordx4 v[224:225], off
	ds_read_b128 v[186:189], v155 offset:16384
	ds_read_b128 v[194:197], v155 offset:17408
	ds_read_b128 v[198:201], v155 offset:18432
	ds_read_b128 v[202:205], v155 offset:19456
	ds_read_b128 v[206:209], v155 offset:20480
	ds_read_b128 v[210:213], v155 offset:21504
	ds_read_b128 v[214:217], v155 offset:22528
	ds_read_b128 v[218:221], v155 offset:23552
	s_waitcnt vmcnt(8)
	s_waitcnt lgkmcnt(0)
	s_barrier
	s_waitcnt lgkmcnt(0)
	v_mfma_f32_16x16x32_bf16 v[52:55], v[144:147], v[186:189], v[52:55]
	v_mfma_f32_16x16x32_bf16 v[48:51], v[162:165], v[186:189], v[48:51]
	v_mfma_f32_16x16x32_bf16 v[36:39], v[144:147], v[198:201], v[36:39]
	v_mfma_f32_16x16x32_bf16 v[32:35], v[162:165], v[198:201], v[32:35]
	v_mfma_f32_16x16x32_bf16 v[20:23], v[144:147], v[206:209], v[20:23]
	v_mfma_f32_16x16x32_bf16 v[16:19], v[162:165], v[206:209], v[16:19]
	v_mfma_f32_16x16x32_bf16 v[4:7], v[144:147], v[214:217], v[4:7]
	v_mfma_f32_16x16x32_bf16 v[0:3], v[162:165], v[214:217], v[0:3]
	v_mfma_f32_16x16x32_bf16 v[52:55], v[158:161], v[194:197], v[52:55]
	v_mfma_f32_16x16x32_bf16 v[48:51], v[166:169], v[194:197], v[48:51]
	v_mfma_f32_16x16x32_bf16 v[36:39], v[158:161], v[202:205], v[36:39]
	v_mfma_f32_16x16x32_bf16 v[32:35], v[166:169], v[202:205], v[32:35]
	v_mfma_f32_16x16x32_bf16 v[20:23], v[158:161], v[210:213], v[20:23]
	v_mfma_f32_16x16x32_bf16 v[16:19], v[166:169], v[210:213], v[16:19]
	v_mfma_f32_16x16x32_bf16 v[4:7], v[158:161], v[218:221], v[4:7]
	v_mfma_f32_16x16x32_bf16 v[0:3], v[166:169], v[218:221], v[0:3]
	v_mfma_f32_16x16x32_bf16 v[60:63], v[170:173], v[186:189], v[60:63]
	v_mfma_f32_16x16x32_bf16 v[56:59], v[178:181], v[186:189], v[56:59]
	v_mfma_f32_16x16x32_bf16 v[44:47], v[170:173], v[198:201], v[44:47]
	v_mfma_f32_16x16x32_bf16 v[40:43], v[178:181], v[198:201], v[40:43]
	v_mfma_f32_16x16x32_bf16 v[28:31], v[170:173], v[206:209], v[28:31]
	v_mfma_f32_16x16x32_bf16 v[24:27], v[178:181], v[206:209], v[24:27]
	v_mfma_f32_16x16x32_bf16 v[12:15], v[170:173], v[214:217], v[12:15]
	v_mfma_f32_16x16x32_bf16 v[8:11], v[178:181], v[214:217], v[8:11]
	v_mfma_f32_16x16x32_bf16 v[60:63], v[174:177], v[194:197], v[60:63]
	v_mfma_f32_16x16x32_bf16 v[56:59], v[182:185], v[194:197], v[56:59]
	v_mfma_f32_16x16x32_bf16 v[44:47], v[174:177], v[202:205], v[44:47]
	v_mfma_f32_16x16x32_bf16 v[40:43], v[182:185], v[202:205], v[40:43]
	v_mfma_f32_16x16x32_bf16 v[28:31], v[174:177], v[210:213], v[28:31]
	v_mfma_f32_16x16x32_bf16 v[24:27], v[182:185], v[210:213], v[24:27]
	v_mfma_f32_16x16x32_bf16 v[12:15], v[174:177], v[218:221], v[12:15]
	v_mfma_f32_16x16x32_bf16 v[8:11], v[182:185], v[218:221], v[8:11]
	s_barrier
	s_add_i32 s33, 0, 0x18000
	s_add_i32 s54, 0, 0x1c000
	s_add_u32 s36, s36, 0x80000
	s_addc_u32 s37, s37, 0
	s_mov_b32 m0, s50
	v_lshl_add_u64 v[226:227], s[36:37], 0, v[134:135]
	global_load_lds_dwordx4 v[226:227], off
	v_lshl_add_u64 v[226:227], s[36:37], 0, v[130:131]
	s_mov_b32 m0, s51
	s_nop 0
	global_load_lds_dwordx4 v[226:227], off
	v_add_u32_e32 v166, s33, v151
	v_add_u32_e32 v182, s54, v151
	ds_read_b128 v[144:147], v166
	ds_read_b128 v[158:161], v166 offset:1024
	ds_read_b128 v[162:165], v166 offset:2048
	ds_read_b128 v[166:169], v166 offset:3072
	ds_read_b128 v[170:173], v182
	ds_read_b128 v[174:177], v182 offset:1024
	ds_read_b128 v[178:181], v182 offset:2048
	ds_read_b128 v[182:185], v182 offset:3072
	ds_read_b128 v[186:189], v155 offset:32768
	ds_read_b128 v[194:197], v155 offset:33792
	ds_read_b128 v[198:201], v155 offset:34816
	ds_read_b128 v[202:205], v155 offset:35840
	ds_read_b128 v[206:209], v155 offset:36864
	ds_read_b128 v[210:213], v155 offset:37888
	ds_read_b128 v[214:217], v155 offset:38912
	ds_read_b128 v[218:221], v155 offset:39936
	s_waitcnt vmcnt(8)
	s_waitcnt lgkmcnt(0)
	s_barrier
	s_waitcnt lgkmcnt(0)
	v_mfma_f32_16x16x32_bf16 v[116:119], v[144:147], v[186:189], v[116:119]
	v_mfma_f32_16x16x32_bf16 v[112:115], v[162:165], v[186:189], v[112:115]
	v_mfma_f32_16x16x32_bf16 v[100:103], v[144:147], v[198:201], v[100:103]
	v_mfma_f32_16x16x32_bf16 v[96:99], v[162:165], v[198:201], v[96:99]
	v_mfma_f32_16x16x32_bf16 v[84:87], v[144:147], v[206:209], v[84:87]
	v_mfma_f32_16x16x32_bf16 v[80:83], v[162:165], v[206:209], v[80:83]
	v_mfma_f32_16x16x32_bf16 v[68:71], v[144:147], v[214:217], v[68:71]
	v_mfma_f32_16x16x32_bf16 v[64:67], v[162:165], v[214:217], v[64:67]
	v_mfma_f32_16x16x32_bf16 v[116:119], v[158:161], v[194:197], v[116:119]
	v_mfma_f32_16x16x32_bf16 v[112:115], v[166:169], v[194:197], v[112:115]
	v_mfma_f32_16x16x32_bf16 v[100:103], v[158:161], v[202:205], v[100:103]
	v_mfma_f32_16x16x32_bf16 v[96:99], v[166:169], v[202:205], v[96:99]
	v_mfma_f32_16x16x32_bf16 v[84:87], v[158:161], v[210:213], v[84:87]
	v_mfma_f32_16x16x32_bf16 v[80:83], v[166:169], v[210:213], v[80:83]
	v_mfma_f32_16x16x32_bf16 v[68:71], v[158:161], v[218:221], v[68:71]
	v_mfma_f32_16x16x32_bf16 v[64:67], v[166:169], v[218:221], v[64:67]
	v_mfma_f32_16x16x32_bf16 v[124:127], v[170:173], v[186:189], v[124:127]
	v_mfma_f32_16x16x32_bf16 v[120:123], v[178:181], v[186:189], v[120:123]
	v_mfma_f32_16x16x32_bf16 v[108:111], v[170:173], v[198:201], v[108:111]
	v_mfma_f32_16x16x32_bf16 v[104:107], v[178:181], v[198:201], v[104:107]
	v_mfma_f32_16x16x32_bf16 v[92:95], v[170:173], v[206:209], v[92:95]
	v_mfma_f32_16x16x32_bf16 v[88:91], v[178:181], v[206:209], v[88:91]
	v_mfma_f32_16x16x32_bf16 v[76:79], v[170:173], v[214:217], v[76:79]
	v_mfma_f32_16x16x32_bf16 v[72:75], v[178:181], v[214:217], v[72:75]
	v_mfma_f32_16x16x32_bf16 v[124:127], v[174:177], v[194:197], v[124:127]
	v_mfma_f32_16x16x32_bf16 v[120:123], v[182:185], v[194:197], v[120:123]
	v_mfma_f32_16x16x32_bf16 v[108:111], v[174:177], v[202:205], v[108:111]
	v_mfma_f32_16x16x32_bf16 v[104:107], v[182:185], v[202:205], v[104:107]
	v_mfma_f32_16x16x32_bf16 v[92:95], v[174:177], v[210:213], v[92:95]
	v_mfma_f32_16x16x32_bf16 v[88:91], v[182:185], v[210:213], v[88:91]
	v_mfma_f32_16x16x32_bf16 v[76:79], v[174:177], v[218:221], v[76:79]
	v_mfma_f32_16x16x32_bf16 v[72:75], v[182:185], v[218:221], v[72:75]
	s_barrier
	s_add_i32 s33, s33, s42
	v_lshl_add_u64 v[148:149], v[148:149], 0, s[18:19]
	s_mov_b32 m0, s33
	s_nop 0
	global_load_lds_dwordx4 v[148:149], off
	s_add_i32 m0, s33, 0x2000
	s_add_u32 s34, s34, 0x80080
	v_lshl_add_u64 v[148:149], v[190:191], 0, s[18:19]
	s_addc_u32 s35, s35, 0
	s_add_i32 s33, s54, s42
	global_load_lds_dwordx4 v[148:149], off
	v_lshl_add_u64 v[148:149], s[34:35], 0, v[132:133]
	s_mov_b32 m0, s33
	s_nop 0
	global_load_lds_dwordx4 v[148:149], off
	v_lshl_add_u64 v[148:149], s[34:35], 0, v[128:129]
	s_add_i32 m0, s33, 0x2000
	s_nop 0
	global_load_lds_dwordx4 v[148:149], off
	v_lshl_add_u64 v[148:149], v[222:223], 0, s[18:19]
	s_mov_b32 m0, s59
	s_nop 0
	global_load_lds_dwordx4 v[148:149], off
	v_lshl_add_u64 v[148:149], v[224:225], 0, s[18:19]
	s_mov_b32 m0, s60
	s_nop 0
	global_load_lds_dwordx4 v[148:149], off
	ds_read_b128 v[186:189], v155 offset:49152
	ds_read_b128 v[194:197], v155 offset:50176
	ds_read_b128 v[198:201], v155 offset:51200
	ds_read_b128 v[202:205], v155 offset:52224
	ds_read_b128 v[206:209], v155 offset:53248
	ds_read_b128 v[210:213], v155 offset:54272
	ds_read_b128 v[214:217], v155 offset:55296
	ds_read_b128 v[218:221], v155 offset:56320
	s_waitcnt vmcnt(8)
	s_waitcnt lgkmcnt(0)
	s_barrier
	s_waitcnt lgkmcnt(0)
	v_mfma_f32_16x16x32_bf16 v[52:55], v[144:147], v[186:189], v[52:55]
	v_mfma_f32_16x16x32_bf16 v[48:51], v[162:165], v[186:189], v[48:51]
	v_mfma_f32_16x16x32_bf16 v[36:39], v[144:147], v[198:201], v[36:39]
	v_mfma_f32_16x16x32_bf16 v[32:35], v[162:165], v[198:201], v[32:35]
	v_mfma_f32_16x16x32_bf16 v[20:23], v[144:147], v[206:209], v[20:23]
	v_mfma_f32_16x16x32_bf16 v[16:19], v[162:165], v[206:209], v[16:19]
	v_mfma_f32_16x16x32_bf16 v[4:7], v[144:147], v[214:217], v[4:7]
	v_mfma_f32_16x16x32_bf16 v[0:3], v[162:165], v[214:217], v[0:3]
	v_mfma_f32_16x16x32_bf16 v[52:55], v[158:161], v[194:197], v[52:55]
	v_mfma_f32_16x16x32_bf16 v[48:51], v[166:169], v[194:197], v[48:51]
	v_mfma_f32_16x16x32_bf16 v[36:39], v[158:161], v[202:205], v[36:39]
	v_mfma_f32_16x16x32_bf16 v[32:35], v[166:169], v[202:205], v[32:35]
	v_mfma_f32_16x16x32_bf16 v[20:23], v[158:161], v[210:213], v[20:23]
	v_mfma_f32_16x16x32_bf16 v[16:19], v[166:169], v[210:213], v[16:19]
	v_mfma_f32_16x16x32_bf16 v[4:7], v[158:161], v[218:221], v[4:7]
	v_mfma_f32_16x16x32_bf16 v[0:3], v[166:169], v[218:221], v[0:3]
	v_mfma_f32_16x16x32_bf16 v[60:63], v[170:173], v[186:189], v[60:63]
	v_mfma_f32_16x16x32_bf16 v[56:59], v[178:181], v[186:189], v[56:59]
	v_mfma_f32_16x16x32_bf16 v[44:47], v[170:173], v[198:201], v[44:47]
	v_mfma_f32_16x16x32_bf16 v[40:43], v[178:181], v[198:201], v[40:43]
	v_mfma_f32_16x16x32_bf16 v[28:31], v[170:173], v[206:209], v[28:31]
	v_mfma_f32_16x16x32_bf16 v[24:27], v[178:181], v[206:209], v[24:27]
	v_mfma_f32_16x16x32_bf16 v[12:15], v[170:173], v[214:217], v[12:15]
	v_mfma_f32_16x16x32_bf16 v[8:11], v[178:181], v[214:217], v[8:11]
	v_mfma_f32_16x16x32_bf16 v[60:63], v[174:177], v[194:197], v[60:63]
	v_mfma_f32_16x16x32_bf16 v[56:59], v[182:185], v[194:197], v[56:59]
	v_mfma_f32_16x16x32_bf16 v[44:47], v[174:177], v[202:205], v[44:47]
	v_mfma_f32_16x16x32_bf16 v[40:43], v[182:185], v[202:205], v[40:43]
	v_mfma_f32_16x16x32_bf16 v[28:31], v[174:177], v[210:213], v[28:31]
	v_mfma_f32_16x16x32_bf16 v[24:27], v[182:185], v[210:213], v[24:27]
	v_mfma_f32_16x16x32_bf16 v[12:15], v[174:177], v[218:221], v[12:15]
	v_mfma_f32_16x16x32_bf16 v[8:11], v[182:185], v[218:221], v[8:11]
	s_barrier
	s_add_i32 s69, s69, 2
	s_add_u32 s30, s30, 0x100
	s_addc_u32 s31, s31, 0
	s_add_u32 s67, s67, 0x100
	s_addc_u32 s68, s68, 0
	s_cmp_gt_u32 s69, 29
	s_cbranch_scc0 .LBB0_673
	v_lshl_add_u32 v144, s8, 8, v150
	v_ashrrev_i32_e32 v145, 31, v144
	v_lshl_add_u64 v[148:149], v[144:145], 2, s[16:17]
	global_load_dword v172, v[148:149], off
	global_load_dword v173, v[148:149], off offset:64
	global_load_dword v174, v[148:149], off offset:128
	global_load_dword v175, v[148:149], off offset:192
	global_load_dword v176, v[148:149], off offset:512
	global_load_dword v177, v[148:149], off offset:576
	global_load_dword v178, v[148:149], off offset:640
	global_load_dword v179, v[148:149], off offset:704
	s_and_b64 vcc, exec, s[20:21]
	s_cbranch_vccz .LBB0_676
	s_barrier

.LBB0_1187:
	s_add_u32 s30, s28, 0x100
	s_addc_u32 s31, s29, 0
	s_cmpk_eq_i32 s68, 0x54
	s_cselect_b32 s37, s11, s31
	s_cselect_b32 s36, s10, s30
	s_cselect_b32 s35, s27, s67
	s_cselect_b32 s34, s26, s66
	v_lshl_add_u64 v[156:157], s[28:29], 0, v[136:137]
	s_add_i32 m0, s43, 0xc000
	s_nop 0
	global_load_lds_dwordx4 v[156:157], off
	v_lshl_add_u64 v[156:157], s[28:29], 0, v[138:139]
	s_add_i32 m0, s43, 0xe000
	s_nop 0
	global_load_lds_dwordx4 v[156:157], off
	ds_read_b128 v[152:155], v161
	ds_read_b128 v[166:169], v161 offset:1024
	ds_read_b128 v[170:173], v161 offset:2048
	ds_read_b128 v[174:177], v161 offset:3072
	ds_read_b128 v[178:181], v162
	ds_read_b128 v[182:185], v162 offset:1024
	ds_read_b128 v[186:189], v162 offset:2048
	ds_read_b128 v[194:197], v162 offset:3072
	ds_read_b128 v[198:201], v163
	ds_read_b128 v[202:205], v163 offset:1024
	ds_read_b128 v[206:209], v163 offset:2048
	ds_read_b128 v[210:213], v163 offset:3072
	ds_read_b128 v[214:217], v163 offset:4096
	ds_read_b128 v[218:221], v163 offset:5120
	ds_read_b128 v[222:225], v163 offset:6144
	ds_read_b128 v[226:229], v163 offset:7168
	s_waitcnt vmcnt(8)
	s_waitcnt lgkmcnt(0)
	s_barrier
	s_waitcnt lgkmcnt(0)
	v_mfma_f32_16x16x32_bf16 v[124:127], v[152:155], v[198:201], v[124:127]
	v_mfma_f32_16x16x32_bf16 v[120:123], v[170:173], v[198:201], v[120:123]
	v_mfma_f32_16x16x32_bf16 v[108:111], v[152:155], v[206:209], v[108:111]
	v_mfma_f32_16x16x32_bf16 v[104:107], v[170:173], v[206:209], v[104:107]
	v_mfma_f32_16x16x32_bf16 v[92:95], v[152:155], v[214:217], v[92:95]
	v_mfma_f32_16x16x32_bf16 v[88:91], v[170:173], v[214:217], v[88:91]
	v_mfma_f32_16x16x32_bf16 v[76:79], v[152:155], v[222:225], v[76:79]
	v_mfma_f32_16x16x32_bf16 v[72:75], v[170:173], v[222:225], v[72:75]
	v_mfma_f32_16x16x32_bf16 v[124:127], v[166:169], v[202:205], v[124:127]
	v_mfma_f32_16x16x32_bf16 v[120:123], v[174:177], v[202:205], v[120:123]
	v_mfma_f32_16x16x32_bf16 v[108:111], v[166:169], v[210:213], v[108:111]
	v_mfma_f32_16x16x32_bf16 v[104:107], v[174:177], v[210:213], v[104:107]
	v_mfma_f32_16x16x32_bf16 v[92:95], v[166:169], v[218:221], v[92:95]
	v_mfma_f32_16x16x32_bf16 v[88:91], v[174:177], v[218:221], v[88:91]
	v_mfma_f32_16x16x32_bf16 v[76:79], v[166:169], v[226:229], v[76:79]
	v_mfma_f32_16x16x32_bf16 v[72:75], v[174:177], v[226:229], v[72:75]
	v_mfma_f32_16x16x32_bf16 v[116:119], v[178:181], v[198:201], v[116:119]
	v_mfma_f32_16x16x32_bf16 v[112:115], v[186:189], v[198:201], v[112:115]
	v_mfma_f32_16x16x32_bf16 v[100:103], v[178:181], v[206:209], v[100:103]
	v_mfma_f32_16x16x32_bf16 v[96:99], v[186:189], v[206:209], v[96:99]
	v_mfma_f32_16x16x32_bf16 v[84:87], v[178:181], v[214:217], v[84:87]
	v_mfma_f32_16x16x32_bf16 v[80:83], v[186:189], v[214:217], v[80:83]
	v_mfma_f32_16x16x32_bf16 v[68:71], v[178:181], v[222:225], v[68:71]
	v_mfma_f32_16x16x32_bf16 v[64:67], v[186:189], v[222:225], v[64:67]
	v_mfma_f32_16x16x32_bf16 v[116:119], v[182:185], v[202:205], v[116:119]
	v_mfma_f32_16x16x32_bf16 v[112:115], v[194:197], v[202:205], v[112:115]
	v_mfma_f32_16x16x32_bf16 v[100:103], v[182:185], v[210:213], v[100:103]
	v_mfma_f32_16x16x32_bf16 v[96:99], v[194:197], v[210:213], v[96:99]
	v_mfma_f32_16x16x32_bf16 v[84:87], v[182:185], v[218:221], v[84:87]
	v_mfma_f32_16x16x32_bf16 v[80:83], v[194:197], v[218:221], v[80:83]
	v_mfma_f32_16x16x32_bf16 v[68:71], v[182:185], v[226:229], v[68:71]
	v_mfma_f32_16x16x32_bf16 v[64:67], v[194:197], v[226:229], v[64:67]
	s_barrier
	s_add_i32 s28, s60, s42
	v_lshl_add_u64 v[156:157], s[34:35], 0, v[130:131]
	s_mov_b32 m0, s28
	s_nop 0
	global_load_lds_dwordx4 v[156:157], off
	s_add_i32 m0, s28, 0x2000
	s_add_u32 s28, s34, 0x160000
	v_lshl_add_u64 v[190:191], s[34:35], 0, v[134:135]
	s_addc_u32 s29, s35, 0
	s_add_i32 s33, s61, s42
	global_load_lds_dwordx4 v[190:191], off
	v_lshl_add_u64 v[230:231], s[28:29], 0, v[130:131]
	s_mov_b32 m0, s33
	v_lshl_add_u64 v[232:233], s[36:37], 0, v[132:133]
	global_load_lds_dwordx4 v[230:231], off
	v_lshl_add_u64 v[230:231], s[28:29], 0, v[134:135]
	s_add_i32 m0, s33, 0x2000
	s_nop 0
	global_load_lds_dwordx4 v[230:231], off
	v_lshl_add_u64 v[230:231], s[36:37], 0, v[128:129]
	s_mov_b32 m0, s43
	s_nop 0
	global_load_lds_dwordx4 v[230:231], off
	s_mov_b32 m0, s48
	s_nop 0
	global_load_lds_dwordx4 v[232:233], off
	ds_read_b128 v[198:201], v163 offset:16384
	ds_read_b128 v[202:205], v163 offset:17408
	ds_read_b128 v[206:209], v163 offset:18432
	ds_read_b128 v[210:213], v163 offset:19456
	ds_read_b128 v[214:217], v163 offset:20480
	ds_read_b128 v[218:221], v163 offset:21504
	ds_read_b128 v[222:225], v163 offset:22528
	ds_read_b128 v[226:229], v163 offset:23552
	s_waitcnt vmcnt(8)
	s_waitcnt lgkmcnt(0)
	s_barrier
	s_waitcnt lgkmcnt(0)
	v_mfma_f32_16x16x32_bf16 v[60:63], v[152:155], v[198:201], v[60:63]
	v_mfma_f32_16x16x32_bf16 v[56:59], v[170:173], v[198:201], v[56:59]
	v_mfma_f32_16x16x32_bf16 v[44:47], v[152:155], v[206:209], v[44:47]
	v_mfma_f32_16x16x32_bf16 v[40:43], v[170:173], v[206:209], v[40:43]
	v_mfma_f32_16x16x32_bf16 v[28:31], v[152:155], v[214:217], v[28:31]
	v_mfma_f32_16x16x32_bf16 v[24:27], v[170:173], v[214:217], v[24:27]
	v_mfma_f32_16x16x32_bf16 v[12:15], v[152:155], v[222:225], v[12:15]
	v_mfma_f32_16x16x32_bf16 v[8:11], v[170:173], v[222:225], v[8:11]
	v_mfma_f32_16x16x32_bf16 v[60:63], v[166:169], v[202:205], v[60:63]
	v_mfma_f32_16x16x32_bf16 v[56:59], v[174:177], v[202:205], v[56:59]
	v_mfma_f32_16x16x32_bf16 v[44:47], v[166:169], v[210:213], v[44:47]
	v_mfma_f32_16x16x32_bf16 v[40:43], v[174:177], v[210:213], v[40:43]
	v_mfma_f32_16x16x32_bf16 v[28:31], v[166:169], v[218:221], v[28:31]
	v_mfma_f32_16x16x32_bf16 v[24:27], v[174:177], v[218:221], v[24:27]
	v_mfma_f32_16x16x32_bf16 v[12:15], v[166:169], v[226:229], v[12:15]
	v_mfma_f32_16x16x32_bf16 v[8:11], v[174:177], v[226:229], v[8:11]
	v_mfma_f32_16x16x32_bf16 v[52:55], v[178:181], v[198:201], v[52:55]
	v_mfma_f32_16x16x32_bf16 v[48:51], v[186:189], v[198:201], v[48:51]
	v_mfma_f32_16x16x32_bf16 v[36:39], v[178:181], v[206:209], v[36:39]
	v_mfma_f32_16x16x32_bf16 v[32:35], v[186:189], v[206:209], v[32:35]
	v_mfma_f32_16x16x32_bf16 v[20:23], v[178:181], v[214:217], v[20:23]
	v_mfma_f32_16x16x32_bf16 v[16:19], v[186:189], v[214:217], v[16:19]
	v_mfma_f32_16x16x32_bf16 v[4:7], v[178:181], v[222:225], v[4:7]
	v_mfma_f32_16x16x32_bf16 v[0:3], v[186:189], v[222:225], v[0:3]
	v_mfma_f32_16x16x32_bf16 v[52:55], v[182:185], v[202:205], v[52:55]
	v_mfma_f32_16x16x32_bf16 v[48:51], v[194:197], v[202:205], v[48:51]
	v_mfma_f32_16x16x32_bf16 v[36:39], v[182:185], v[210:213], v[36:39]
	v_mfma_f32_16x16x32_bf16 v[32:35], v[194:197], v[210:213], v[32:35]
	v_mfma_f32_16x16x32_bf16 v[20:23], v[182:185], v[218:221], v[20:23]
	v_mfma_f32_16x16x32_bf16 v[16:19], v[194:197], v[218:221], v[16:19]
	v_mfma_f32_16x16x32_bf16 v[4:7], v[182:185], v[226:229], v[4:7]
	v_mfma_f32_16x16x32_bf16 v[0:3], v[194:197], v[226:229], v[0:3]
	s_barrier
	s_add_i32 s33, 0, 0x18000
	s_add_i32 s54, 0, 0x1c000
	s_add_u32 s28, s36, 0x160000
	s_addc_u32 s29, s37, 0
	s_mov_b32 m0, s49
	v_lshl_add_u64 v[234:235], s[28:29], 0, v[128:129]
	global_load_lds_dwordx4 v[234:235], off
	v_lshl_add_u64 v[234:235], s[28:29], 0, v[132:133]
	s_mov_b32 m0, s50
	s_nop 0
	global_load_lds_dwordx4 v[234:235], off
	v_add_u32_e32 v165, s33, v159
	ds_read_b128 v[152:155], v165
	ds_read_b128 v[166:169], v165 offset:1024
	ds_read_b128 v[170:173], v165 offset:2048
	ds_read_b128 v[174:177], v165 offset:3072
	v_add_u32_e32 v165, s54, v159
	ds_read_b128 v[178:181], v165
	ds_read_b128 v[182:185], v165 offset:1024
	ds_read_b128 v[186:189], v165 offset:2048
	ds_read_b128 v[194:197], v165 offset:3072
	ds_read_b128 v[198:201], v163 offset:32768
	ds_read_b128 v[202:205], v163 offset:33792
	ds_read_b128 v[206:209], v163 offset:34816
	ds_read_b128 v[210:213], v163 offset:35840
	ds_read_b128 v[214:217], v163 offset:36864
	ds_read_b128 v[218:221], v163 offset:37888
	ds_read_b128 v[222:225], v163 offset:38912
	ds_read_b128 v[226:229], v163 offset:39936
	s_waitcnt vmcnt(8)
	s_waitcnt lgkmcnt(0)
	s_barrier
	s_waitcnt lgkmcnt(0)
	v_mfma_f32_16x16x32_bf16 v[124:127], v[152:155], v[198:201], v[124:127]
	v_mfma_f32_16x16x32_bf16 v[120:123], v[170:173], v[198:201], v[120:123]
	v_mfma_f32_16x16x32_bf16 v[108:111], v[152:155], v[206:209], v[108:111]
	v_mfma_f32_16x16x32_bf16 v[104:107], v[170:173], v[206:209], v[104:107]
	v_mfma_f32_16x16x32_bf16 v[92:95], v[152:155], v[214:217], v[92:95]
	v_mfma_f32_16x16x32_bf16 v[88:91], v[170:173], v[214:217], v[88:91]
	v_mfma_f32_16x16x32_bf16 v[76:79], v[152:155], v[222:225], v[76:79]
	v_mfma_f32_16x16x32_bf16 v[72:75], v[170:173], v[222:225], v[72:75]
	v_mfma_f32_16x16x32_bf16 v[124:127], v[166:169], v[202:205], v[124:127]
	v_mfma_f32_16x16x32_bf16 v[120:123], v[174:177], v[202:205], v[120:123]
	v_mfma_f32_16x16x32_bf16 v[108:111], v[166:169], v[210:213], v[108:111]
	v_mfma_f32_16x16x32_bf16 v[104:107], v[174:177], v[210:213], v[104:107]
	v_mfma_f32_16x16x32_bf16 v[92:95], v[166:169], v[218:221], v[92:95]
	v_mfma_f32_16x16x32_bf16 v[88:91], v[174:177], v[218:221], v[88:91]
	v_mfma_f32_16x16x32_bf16 v[76:79], v[166:169], v[226:229], v[76:79]
	v_mfma_f32_16x16x32_bf16 v[72:75], v[174:177], v[226:229], v[72:75]
	v_mfma_f32_16x16x32_bf16 v[116:119], v[178:181], v[198:201], v[116:119]
	v_mfma_f32_16x16x32_bf16 v[112:115], v[186:189], v[198:201], v[112:115]
	v_mfma_f32_16x16x32_bf16 v[100:103], v[178:181], v[206:209], v[100:103]
	v_mfma_f32_16x16x32_bf16 v[96:99], v[186:189], v[206:209], v[96:99]
	v_mfma_f32_16x16x32_bf16 v[84:87], v[178:181], v[214:217], v[84:87]
	v_mfma_f32_16x16x32_bf16 v[80:83], v[186:189], v[214:217], v[80:83]
	v_mfma_f32_16x16x32_bf16 v[68:71], v[178:181], v[222:225], v[68:71]
	v_mfma_f32_16x16x32_bf16 v[64:67], v[186:189], v[222:225], v[64:67]
	v_mfma_f32_16x16x32_bf16 v[116:119], v[182:185], v[202:205], v[116:119]
	v_mfma_f32_16x16x32_bf16 v[112:115], v[194:197], v[202:205], v[112:115]
	v_mfma_f32_16x16x32_bf16 v[100:103], v[182:185], v[210:213], v[100:103]
	v_mfma_f32_16x16x32_bf16 v[96:99], v[194:197], v[210:213], v[96:99]
	v_mfma_f32_16x16x32_bf16 v[84:87], v[182:185], v[218:221], v[84:87]
	v_mfma_f32_16x16x32_bf16 v[80:83], v[194:197], v[218:221], v[80:83]
	v_mfma_f32_16x16x32_bf16 v[68:71], v[182:185], v[226:229], v[68:71]
	v_mfma_f32_16x16x32_bf16 v[64:67], v[194:197], v[226:229], v[64:67]
	s_barrier
	s_add_i32 s28, s33, s42
	v_lshl_add_u64 v[156:157], v[156:157], 0, s[22:23]
	s_mov_b32 m0, s28
	s_nop 0
	global_load_lds_dwordx4 v[156:157], off
	s_add_i32 m0, s28, 0x2000
	s_add_u32 s28, s34, 0x160080
	v_lshl_add_u64 v[156:157], v[190:191], 0, s[22:23]
	s_addc_u32 s29, s35, 0
	s_add_i32 s33, s54, s42
	global_load_lds_dwordx4 v[156:157], off
	v_lshl_add_u64 v[156:157], s[28:29], 0, v[130:131]
	s_mov_b32 m0, s33
	s_nop 0
	global_load_lds_dwordx4 v[156:157], off
	v_lshl_add_u64 v[156:157], s[28:29], 0, v[134:135]
	s_add_i32 m0, s33, 0x2000
	s_nop 0
	global_load_lds_dwordx4 v[156:157], off
	v_lshl_add_u64 v[156:157], v[230:231], 0, s[22:23]
	s_mov_b32 m0, s58
	s_nop 0
	global_load_lds_dwordx4 v[156:157], off
	v_lshl_add_u64 v[156:157], v[232:233], 0, s[22:23]
	s_mov_b32 m0, s59
	s_nop 0
	global_load_lds_dwordx4 v[156:157], off
	ds_read_b128 v[198:201], v163 offset:49152
	ds_read_b128 v[202:205], v163 offset:50176
	ds_read_b128 v[206:209], v163 offset:51200
	ds_read_b128 v[210:213], v163 offset:52224
	ds_read_b128 v[214:217], v163 offset:53248
	ds_read_b128 v[218:221], v163 offset:54272
	ds_read_b128 v[222:225], v163 offset:55296
	ds_read_b128 v[226:229], v163 offset:56320
	s_waitcnt vmcnt(8)
	s_waitcnt lgkmcnt(0)
	s_barrier
	s_waitcnt lgkmcnt(0)
	v_mfma_f32_16x16x32_bf16 v[60:63], v[152:155], v[198:201], v[60:63]
	v_mfma_f32_16x16x32_bf16 v[56:59], v[170:173], v[198:201], v[56:59]
	v_mfma_f32_16x16x32_bf16 v[44:47], v[152:155], v[206:209], v[44:47]
	v_mfma_f32_16x16x32_bf16 v[40:43], v[170:173], v[206:209], v[40:43]
	v_mfma_f32_16x16x32_bf16 v[28:31], v[152:155], v[214:217], v[28:31]
	v_mfma_f32_16x16x32_bf16 v[24:27], v[170:173], v[214:217], v[24:27]
	v_mfma_f32_16x16x32_bf16 v[12:15], v[152:155], v[222:225], v[12:15]
	v_mfma_f32_16x16x32_bf16 v[8:11], v[170:173], v[222:225], v[8:11]
	v_mfma_f32_16x16x32_bf16 v[60:63], v[166:169], v[202:205], v[60:63]
	v_mfma_f32_16x16x32_bf16 v[56:59], v[174:177], v[202:205], v[56:59]
	v_mfma_f32_16x16x32_bf16 v[44:47], v[166:169], v[210:213], v[44:47]
	v_mfma_f32_16x16x32_bf16 v[40:43], v[174:177], v[210:213], v[40:43]
	v_mfma_f32_16x16x32_bf16 v[28:31], v[166:169], v[218:221], v[28:31]
	v_mfma_f32_16x16x32_bf16 v[24:27], v[174:177], v[218:221], v[24:27]
	v_mfma_f32_16x16x32_bf16 v[12:15], v[166:169], v[226:229], v[12:15]
	v_mfma_f32_16x16x32_bf16 v[8:11], v[174:177], v[226:229], v[8:11]
	v_mfma_f32_16x16x32_bf16 v[52:55], v[178:181], v[198:201], v[52:55]
	v_mfma_f32_16x16x32_bf16 v[48:51], v[186:189], v[198:201], v[48:51]
	v_mfma_f32_16x16x32_bf16 v[36:39], v[178:181], v[206:209], v[36:39]
	v_mfma_f32_16x16x32_bf16 v[32:35], v[186:189], v[206:209], v[32:35]
	v_mfma_f32_16x16x32_bf16 v[20:23], v[178:181], v[214:217], v[20:23]
	v_mfma_f32_16x16x32_bf16 v[16:19], v[186:189], v[214:217], v[16:19]
	v_mfma_f32_16x16x32_bf16 v[4:7], v[178:181], v[222:225], v[4:7]
	v_mfma_f32_16x16x32_bf16 v[0:3], v[186:189], v[222:225], v[0:3]
	v_mfma_f32_16x16x32_bf16 v[52:55], v[182:185], v[202:205], v[52:55]
	v_mfma_f32_16x16x32_bf16 v[48:51], v[194:197], v[202:205], v[48:51]
	v_mfma_f32_16x16x32_bf16 v[36:39], v[182:185], v[210:213], v[36:39]
	v_mfma_f32_16x16x32_bf16 v[32:35], v[194:197], v[210:213], v[32:35]
	v_mfma_f32_16x16x32_bf16 v[20:23], v[182:185], v[218:221], v[20:23]
	v_mfma_f32_16x16x32_bf16 v[16:19], v[194:197], v[218:221], v[16:19]
	v_mfma_f32_16x16x32_bf16 v[4:7], v[182:185], v[226:229], v[4:7]
	v_mfma_f32_16x16x32_bf16 v[0:3], v[194:197], v[226:229], v[0:3]
	s_barrier
	s_add_i32 s68, s68, 2
	s_add_u32 s66, s66, 0x100
	s_addc_u32 s67, s67, 0
	s_cmpk_gt_u32 s68, 0x55
	s_mov_b64 s[28:29], s[30:31]
	s_cbranch_scc0 .LBB0_1187
	v_lshl_add_u32 v156, s64, 8, v158
	v_lshl_or_b32 v154, s65, 8, v160
	v_ashrrev_i32_e32 v157, 31, v156
	v_ashrrev_i32_e32 v155, 31, v154
	v_lshlrev_b64 v[152:153], 11, v[156:157]
	v_lshl_add_u64 v[152:153], v[152:153], 0, v[154:155]
	v_lshlrev_b64 v[170:171], 1, v[152:153]
	v_lshl_add_u64 v[172:173], s[16:17], 0, v[170:171]
	global_load_dwordx4 v[180:183], v[172:173], off
	global_load_dwordx4 v[184:187], v[172:173], off offset:256
	v_add_co_u32_e32 v252, vcc, 0x10000, v172
	s_nop 1
	v_addc_co_u32_e32 v253, vcc, 0, v173, vcc
	global_load_dwordx4 v[188:191], v[252:253], off
	global_load_dwordx4 v[194:197], v[252:253], off offset:256
	v_add_co_u32_e32 v254, vcc, 0x20000, v172
	s_nop 1
	v_addc_co_u32_e32 v255, vcc, 0, v173, vcc
	global_load_dwordx4 v[198:201], v[254:255], off
	global_load_dwordx4 v[202:205], v[254:255], off offset:256
	v_add_co_u32_e32 v252, vcc, 0x30000, v172
	s_nop 1
	v_addc_co_u32_e32 v253, vcc, 0, v173, vcc
	global_load_dwordx4 v[206:209], v[252:253], off
	global_load_dwordx4 v[210:213], v[252:253], off offset:256
	v_add_co_u32_e32 v254, vcc, 0x80000, v172
	s_nop 1
	v_addc_co_u32_e32 v255, vcc, 0, v173, vcc
	global_load_dwordx4 v[214:217], v[254:255], off
	global_load_dwordx4 v[218:221], v[254:255], off offset:256
	v_add_co_u32_e32 v252, vcc, 0x90000, v172
	s_nop 1
	v_addc_co_u32_e32 v253, vcc, 0, v173, vcc
	global_load_dwordx4 v[222:225], v[252:253], off
	global_load_dwordx4 v[226:229], v[252:253], off offset:256
	v_add_co_u32_e32 v254, vcc, 0xa0000, v172
	s_nop 1
	v_addc_co_u32_e32 v255, vcc, 0, v173, vcc
	global_load_dwordx4 v[230:233], v[254:255], off
	global_load_dwordx4 v[234:237], v[254:255], off offset:256
	v_add_co_u32_e32 v252, vcc, 0xb0000, v172
	s_nop 1
	v_addc_co_u32_e32 v253, vcc, 0, v173, vcc
	global_load_dwordx4 v[238:241], v[252:253], off
	global_load_dwordx4 v[242:245], v[252:253], off offset:256
	s_and_b64 vcc, exec, s[24:25]
	s_cbranch_vccz .LBB0_1190
	s_barrier

.LBB0_1271:
	s_add_u32 s33, s30, 0xfff80080
	s_addc_u32 s34, s31, -1
	s_cmp_eq_u32 s67, 28
	s_cselect_b32 s37, s25, s34
	s_cselect_b32 s36, s63, s33
	s_cselect_b32 s35, s23, s66
	s_cselect_b32 s34, s64, s65
	v_lshl_add_u64 v[218:219], s[30:31], 0, v[136:137]
	s_add_i32 m0, s48, 0xc000
	s_nop 0
	global_load_lds_dwordx4 v[218:219], off
	v_lshl_add_u64 v[218:219], s[30:31], 0, v[138:139]
	s_add_i32 m0, s48, 0xe000
	s_nop 0
	global_load_lds_dwordx4 v[218:219], off
	ds_read_b128 v[144:147], v155
	ds_read_b128 v[148:151], v155 offset:1024
	ds_read_b128 v[160:163], v155 offset:2048
	ds_read_b128 v[164:167], v155 offset:3072
	ds_read_b128 v[168:171], v156
	ds_read_b128 v[172:175], v156 offset:1024
	ds_read_b128 v[176:179], v156 offset:2048
	ds_read_b128 v[180:183], v156 offset:3072
	ds_read_b128 v[184:187], v157
	ds_read_b128 v[188:191], v157 offset:1024
	ds_read_b128 v[194:197], v157 offset:2048
	ds_read_b128 v[198:201], v157 offset:3072
	ds_read_b128 v[202:205], v157 offset:4096
	ds_read_b128 v[206:209], v157 offset:5120
	ds_read_b128 v[210:213], v157 offset:6144
	ds_read_b128 v[214:217], v157 offset:7168
	s_waitcnt vmcnt(8)
	s_waitcnt lgkmcnt(0)
	s_barrier
	s_waitcnt lgkmcnt(0)
	v_mfma_f32_16x16x32_bf16 v[124:127], v[144:147], v[184:187], v[124:127]
	v_mfma_f32_16x16x32_bf16 v[120:123], v[160:163], v[184:187], v[120:123]
	v_mfma_f32_16x16x32_bf16 v[108:111], v[144:147], v[194:197], v[108:111]
	v_mfma_f32_16x16x32_bf16 v[104:107], v[160:163], v[194:197], v[104:107]
	v_mfma_f32_16x16x32_bf16 v[92:95], v[144:147], v[202:205], v[92:95]
	v_mfma_f32_16x16x32_bf16 v[88:91], v[160:163], v[202:205], v[88:91]
	v_mfma_f32_16x16x32_bf16 v[76:79], v[144:147], v[210:213], v[76:79]
	v_mfma_f32_16x16x32_bf16 v[72:75], v[160:163], v[210:213], v[72:75]
	v_mfma_f32_16x16x32_bf16 v[124:127], v[148:151], v[188:191], v[124:127]
	v_mfma_f32_16x16x32_bf16 v[120:123], v[164:167], v[188:191], v[120:123]
	v_mfma_f32_16x16x32_bf16 v[108:111], v[148:151], v[198:201], v[108:111]
	v_mfma_f32_16x16x32_bf16 v[104:107], v[164:167], v[198:201], v[104:107]
	v_mfma_f32_16x16x32_bf16 v[92:95], v[148:151], v[206:209], v[92:95]
	v_mfma_f32_16x16x32_bf16 v[88:91], v[164:167], v[206:209], v[88:91]
	v_mfma_f32_16x16x32_bf16 v[76:79], v[148:151], v[214:217], v[76:79]
	v_mfma_f32_16x16x32_bf16 v[72:75], v[164:167], v[214:217], v[72:75]
	v_mfma_f32_16x16x32_bf16 v[116:119], v[168:171], v[184:187], v[116:119]
	v_mfma_f32_16x16x32_bf16 v[112:115], v[176:179], v[184:187], v[112:115]
	v_mfma_f32_16x16x32_bf16 v[100:103], v[168:171], v[194:197], v[100:103]
	v_mfma_f32_16x16x32_bf16 v[96:99], v[176:179], v[194:197], v[96:99]
	v_mfma_f32_16x16x32_bf16 v[84:87], v[168:171], v[202:205], v[84:87]
	v_mfma_f32_16x16x32_bf16 v[80:83], v[176:179], v[202:205], v[80:83]
	v_mfma_f32_16x16x32_bf16 v[68:71], v[168:171], v[210:213], v[68:71]
	v_mfma_f32_16x16x32_bf16 v[64:67], v[176:179], v[210:213], v[64:67]
	v_mfma_f32_16x16x32_bf16 v[116:119], v[172:175], v[188:191], v[116:119]
	v_mfma_f32_16x16x32_bf16 v[112:115], v[180:183], v[188:191], v[112:115]
	v_mfma_f32_16x16x32_bf16 v[100:103], v[172:175], v[198:201], v[100:103]
	v_mfma_f32_16x16x32_bf16 v[96:99], v[180:183], v[198:201], v[96:99]
	v_mfma_f32_16x16x32_bf16 v[84:87], v[172:175], v[206:209], v[84:87]
	v_mfma_f32_16x16x32_bf16 v[80:83], v[180:183], v[206:209], v[80:83]
	v_mfma_f32_16x16x32_bf16 v[68:71], v[172:175], v[214:217], v[68:71]
	v_mfma_f32_16x16x32_bf16 v[64:67], v[180:183], v[214:217], v[64:67]
	s_barrier
	s_add_i32 s33, s59, s42
	v_lshl_add_u64 v[218:219], s[34:35], 0, v[132:133]
	s_mov_b32 m0, s33
	s_nop 0
	global_load_lds_dwordx4 v[218:219], off
	s_add_i32 m0, s33, 0x2000
	s_add_u32 s54, s34, 0x80000
	v_lshl_add_u64 v[220:221], s[34:35], 0, v[128:129]
	s_addc_u32 s55, s35, 0
	s_add_i32 s33, s60, s42
	global_load_lds_dwordx4 v[220:221], off
	v_lshl_add_u64 v[222:223], s[54:55], 0, v[132:133]
	s_mov_b32 m0, s33
	v_lshl_add_u64 v[224:225], s[36:37], 0, v[130:131]
	global_load_lds_dwordx4 v[222:223], off
	v_lshl_add_u64 v[222:223], s[54:55], 0, v[128:129]
	s_add_i32 m0, s33, 0x2000
	s_nop 0
	global_load_lds_dwordx4 v[222:223], off
	v_lshl_add_u64 v[222:223], s[36:37], 0, v[134:135]
	s_mov_b32 m0, s48
	s_nop 0
	global_load_lds_dwordx4 v[222:223], off
	s_mov_b32 m0, s49
	s_nop 0
	global_load_lds_dwordx4 v[224:225], off
	ds_read_b128 v[184:187], v157 offset:16384
	ds_read_b128 v[188:191], v157 offset:17408
	ds_read_b128 v[194:197], v157 offset:18432
	ds_read_b128 v[198:201], v157 offset:19456
	ds_read_b128 v[202:205], v157 offset:20480
	ds_read_b128 v[206:209], v157 offset:21504
	ds_read_b128 v[210:213], v157 offset:22528
	ds_read_b128 v[214:217], v157 offset:23552
	s_waitcnt vmcnt(8)
	s_waitcnt lgkmcnt(0)
	s_barrier
	s_waitcnt lgkmcnt(0)
	v_mfma_f32_16x16x32_bf16 v[60:63], v[144:147], v[184:187], v[60:63]
	v_mfma_f32_16x16x32_bf16 v[56:59], v[160:163], v[184:187], v[56:59]
	v_mfma_f32_16x16x32_bf16 v[44:47], v[144:147], v[194:197], v[44:47]
	v_mfma_f32_16x16x32_bf16 v[40:43], v[160:163], v[194:197], v[40:43]
	v_mfma_f32_16x16x32_bf16 v[28:31], v[144:147], v[202:205], v[28:31]
	v_mfma_f32_16x16x32_bf16 v[24:27], v[160:163], v[202:205], v[24:27]
	v_mfma_f32_16x16x32_bf16 v[12:15], v[144:147], v[210:213], v[12:15]
	v_mfma_f32_16x16x32_bf16 v[8:11], v[160:163], v[210:213], v[8:11]
	v_mfma_f32_16x16x32_bf16 v[60:63], v[148:151], v[188:191], v[60:63]
	v_mfma_f32_16x16x32_bf16 v[56:59], v[164:167], v[188:191], v[56:59]
	v_mfma_f32_16x16x32_bf16 v[44:47], v[148:151], v[198:201], v[44:47]
	v_mfma_f32_16x16x32_bf16 v[40:43], v[164:167], v[198:201], v[40:43]
	v_mfma_f32_16x16x32_bf16 v[28:31], v[148:151], v[206:209], v[28:31]
	v_mfma_f32_16x16x32_bf16 v[24:27], v[164:167], v[206:209], v[24:27]
	v_mfma_f32_16x16x32_bf16 v[12:15], v[148:151], v[214:217], v[12:15]
	v_mfma_f32_16x16x32_bf16 v[8:11], v[164:167], v[214:217], v[8:11]
	v_mfma_f32_16x16x32_bf16 v[52:55], v[168:171], v[184:187], v[52:55]
	v_mfma_f32_16x16x32_bf16 v[48:51], v[176:179], v[184:187], v[48:51]
	v_mfma_f32_16x16x32_bf16 v[36:39], v[168:171], v[194:197], v[36:39]
	v_mfma_f32_16x16x32_bf16 v[32:35], v[176:179], v[194:197], v[32:35]
	v_mfma_f32_16x16x32_bf16 v[20:23], v[168:171], v[202:205], v[20:23]
	v_mfma_f32_16x16x32_bf16 v[16:19], v[176:179], v[202:205], v[16:19]
	v_mfma_f32_16x16x32_bf16 v[4:7], v[168:171], v[210:213], v[4:7]
	v_mfma_f32_16x16x32_bf16 v[0:3], v[176:179], v[210:213], v[0:3]
	v_mfma_f32_16x16x32_bf16 v[52:55], v[172:175], v[188:191], v[52:55]
	v_mfma_f32_16x16x32_bf16 v[48:51], v[180:183], v[188:191], v[48:51]
	v_mfma_f32_16x16x32_bf16 v[36:39], v[172:175], v[198:201], v[36:39]
	v_mfma_f32_16x16x32_bf16 v[32:35], v[180:183], v[198:201], v[32:35]
	v_mfma_f32_16x16x32_bf16 v[20:23], v[172:175], v[206:209], v[20:23]
	v_mfma_f32_16x16x32_bf16 v[16:19], v[180:183], v[206:209], v[16:19]
	v_mfma_f32_16x16x32_bf16 v[4:7], v[172:175], v[214:217], v[4:7]
	v_mfma_f32_16x16x32_bf16 v[0:3], v[180:183], v[214:217], v[0:3]
	s_barrier
	s_add_i32 s33, 0, 0x18000
	s_add_i32 s54, 0, 0x1c000
	s_add_u32 s36, s36, 0x80000
	s_addc_u32 s37, s37, 0
	s_mov_b32 m0, s50
	v_lshl_add_u64 v[226:227], s[36:37], 0, v[134:135]
	global_load_lds_dwordx4 v[226:227], off
	v_lshl_add_u64 v[226:227], s[36:37], 0, v[130:131]
	s_mov_b32 m0, s51
	s_nop 0
	global_load_lds_dwordx4 v[226:227], off
	v_add_u32_e32 v164, s33, v153
	v_add_u32_e32 v180, s54, v153
	ds_read_b128 v[144:147], v164
	ds_read_b128 v[148:151], v164 offset:1024
	ds_read_b128 v[160:163], v164 offset:2048
	ds_read_b128 v[164:167], v164 offset:3072
	ds_read_b128 v[168:171], v180
	ds_read_b128 v[172:175], v180 offset:1024
	ds_read_b128 v[176:179], v180 offset:2048
	ds_read_b128 v[180:183], v180 offset:3072
	ds_read_b128 v[184:187], v157 offset:32768
	ds_read_b128 v[188:191], v157 offset:33792
	ds_read_b128 v[194:197], v157 offset:34816
	ds_read_b128 v[198:201], v157 offset:35840
	ds_read_b128 v[202:205], v157 offset:36864
	ds_read_b128 v[206:209], v157 offset:37888
	ds_read_b128 v[210:213], v157 offset:38912
	ds_read_b128 v[214:217], v157 offset:39936
	s_waitcnt vmcnt(8)
	s_waitcnt lgkmcnt(0)
	s_barrier
	s_waitcnt lgkmcnt(0)
	v_mfma_f32_16x16x32_bf16 v[124:127], v[144:147], v[184:187], v[124:127]
	v_mfma_f32_16x16x32_bf16 v[120:123], v[160:163], v[184:187], v[120:123]
	v_mfma_f32_16x16x32_bf16 v[108:111], v[144:147], v[194:197], v[108:111]
	v_mfma_f32_16x16x32_bf16 v[104:107], v[160:163], v[194:197], v[104:107]
	v_mfma_f32_16x16x32_bf16 v[92:95], v[144:147], v[202:205], v[92:95]
	v_mfma_f32_16x16x32_bf16 v[88:91], v[160:163], v[202:205], v[88:91]
	v_mfma_f32_16x16x32_bf16 v[76:79], v[144:147], v[210:213], v[76:79]
	v_mfma_f32_16x16x32_bf16 v[72:75], v[160:163], v[210:213], v[72:75]
	v_mfma_f32_16x16x32_bf16 v[124:127], v[148:151], v[188:191], v[124:127]
	v_mfma_f32_16x16x32_bf16 v[120:123], v[164:167], v[188:191], v[120:123]
	v_mfma_f32_16x16x32_bf16 v[108:111], v[148:151], v[198:201], v[108:111]
	v_mfma_f32_16x16x32_bf16 v[104:107], v[164:167], v[198:201], v[104:107]
	v_mfma_f32_16x16x32_bf16 v[92:95], v[148:151], v[206:209], v[92:95]
	v_mfma_f32_16x16x32_bf16 v[88:91], v[164:167], v[206:209], v[88:91]
	v_mfma_f32_16x16x32_bf16 v[76:79], v[148:151], v[214:217], v[76:79]
	v_mfma_f32_16x16x32_bf16 v[72:75], v[164:167], v[214:217], v[72:75]
	v_mfma_f32_16x16x32_bf16 v[116:119], v[168:171], v[184:187], v[116:119]
	v_mfma_f32_16x16x32_bf16 v[112:115], v[176:179], v[184:187], v[112:115]
	v_mfma_f32_16x16x32_bf16 v[100:103], v[168:171], v[194:197], v[100:103]
	v_mfma_f32_16x16x32_bf16 v[96:99], v[176:179], v[194:197], v[96:99]
	v_mfma_f32_16x16x32_bf16 v[84:87], v[168:171], v[202:205], v[84:87]
	v_mfma_f32_16x16x32_bf16 v[80:83], v[176:179], v[202:205], v[80:83]
	v_mfma_f32_16x16x32_bf16 v[68:71], v[168:171], v[210:213], v[68:71]
	v_mfma_f32_16x16x32_bf16 v[64:67], v[176:179], v[210:213], v[64:67]
	v_mfma_f32_16x16x32_bf16 v[116:119], v[172:175], v[188:191], v[116:119]
	v_mfma_f32_16x16x32_bf16 v[112:115], v[180:183], v[188:191], v[112:115]
	v_mfma_f32_16x16x32_bf16 v[100:103], v[172:175], v[198:201], v[100:103]
	v_mfma_f32_16x16x32_bf16 v[96:99], v[180:183], v[198:201], v[96:99]
	v_mfma_f32_16x16x32_bf16 v[84:87], v[172:175], v[206:209], v[84:87]
	v_mfma_f32_16x16x32_bf16 v[80:83], v[180:183], v[206:209], v[80:83]
	v_mfma_f32_16x16x32_bf16 v[68:71], v[172:175], v[214:217], v[68:71]
	v_mfma_f32_16x16x32_bf16 v[64:67], v[180:183], v[214:217], v[64:67]
	s_barrier
	s_add_i32 s33, s33, s42
	v_lshl_add_u64 v[218:219], v[218:219], 0, s[18:19]
	s_mov_b32 m0, s33
	s_nop 0
	global_load_lds_dwordx4 v[218:219], off
	s_add_i32 m0, s33, 0x2000
	s_add_u32 s34, s34, 0x80080
	v_lshl_add_u64 v[218:219], v[220:221], 0, s[18:19]
	s_addc_u32 s35, s35, 0
	s_add_i32 s33, s54, s42
	global_load_lds_dwordx4 v[218:219], off
	v_lshl_add_u64 v[218:219], s[34:35], 0, v[132:133]
	s_mov_b32 m0, s33
	s_nop 0
	global_load_lds_dwordx4 v[218:219], off
	v_lshl_add_u64 v[218:219], s[34:35], 0, v[128:129]
	s_add_i32 m0, s33, 0x2000
	s_nop 0
	global_load_lds_dwordx4 v[218:219], off
	v_lshl_add_u64 v[218:219], v[222:223], 0, s[18:19]
	s_mov_b32 m0, s57
	s_nop 0
	global_load_lds_dwordx4 v[218:219], off
	v_lshl_add_u64 v[218:219], v[224:225], 0, s[18:19]
	s_mov_b32 m0, s58
	s_nop 0
	global_load_lds_dwordx4 v[218:219], off
	ds_read_b128 v[184:187], v157 offset:49152
	ds_read_b128 v[188:191], v157 offset:50176
	ds_read_b128 v[194:197], v157 offset:51200
	ds_read_b128 v[198:201], v157 offset:52224
	ds_read_b128 v[202:205], v157 offset:53248
	ds_read_b128 v[206:209], v157 offset:54272
	ds_read_b128 v[210:213], v157 offset:55296
	ds_read_b128 v[214:217], v157 offset:56320
	s_waitcnt vmcnt(8)
	s_waitcnt lgkmcnt(0)
	s_barrier
	s_waitcnt lgkmcnt(0)
	v_mfma_f32_16x16x32_bf16 v[60:63], v[144:147], v[184:187], v[60:63]
	v_mfma_f32_16x16x32_bf16 v[56:59], v[160:163], v[184:187], v[56:59]
	v_mfma_f32_16x16x32_bf16 v[44:47], v[144:147], v[194:197], v[44:47]
	v_mfma_f32_16x16x32_bf16 v[40:43], v[160:163], v[194:197], v[40:43]
	v_mfma_f32_16x16x32_bf16 v[28:31], v[144:147], v[202:205], v[28:31]
	v_mfma_f32_16x16x32_bf16 v[24:27], v[160:163], v[202:205], v[24:27]
	v_mfma_f32_16x16x32_bf16 v[12:15], v[144:147], v[210:213], v[12:15]
	v_mfma_f32_16x16x32_bf16 v[8:11], v[160:163], v[210:213], v[8:11]
	v_mfma_f32_16x16x32_bf16 v[60:63], v[148:151], v[188:191], v[60:63]
	v_mfma_f32_16x16x32_bf16 v[56:59], v[164:167], v[188:191], v[56:59]
	v_mfma_f32_16x16x32_bf16 v[44:47], v[148:151], v[198:201], v[44:47]
	v_mfma_f32_16x16x32_bf16 v[40:43], v[164:167], v[198:201], v[40:43]
	v_mfma_f32_16x16x32_bf16 v[28:31], v[148:151], v[206:209], v[28:31]
	v_mfma_f32_16x16x32_bf16 v[24:27], v[164:167], v[206:209], v[24:27]
	v_mfma_f32_16x16x32_bf16 v[12:15], v[148:151], v[214:217], v[12:15]
	v_mfma_f32_16x16x32_bf16 v[8:11], v[164:167], v[214:217], v[8:11]
	v_mfma_f32_16x16x32_bf16 v[52:55], v[168:171], v[184:187], v[52:55]
	v_mfma_f32_16x16x32_bf16 v[48:51], v[176:179], v[184:187], v[48:51]
	v_mfma_f32_16x16x32_bf16 v[36:39], v[168:171], v[194:197], v[36:39]
	v_mfma_f32_16x16x32_bf16 v[32:35], v[176:179], v[194:197], v[32:35]
	v_mfma_f32_16x16x32_bf16 v[20:23], v[168:171], v[202:205], v[20:23]
	v_mfma_f32_16x16x32_bf16 v[16:19], v[176:179], v[202:205], v[16:19]
	v_mfma_f32_16x16x32_bf16 v[4:7], v[168:171], v[210:213], v[4:7]
	v_mfma_f32_16x16x32_bf16 v[0:3], v[176:179], v[210:213], v[0:3]
	v_mfma_f32_16x16x32_bf16 v[52:55], v[172:175], v[188:191], v[52:55]
	v_mfma_f32_16x16x32_bf16 v[48:51], v[180:183], v[188:191], v[48:51]
	v_mfma_f32_16x16x32_bf16 v[36:39], v[172:175], v[198:201], v[36:39]
	v_mfma_f32_16x16x32_bf16 v[32:35], v[180:183], v[198:201], v[32:35]
	v_mfma_f32_16x16x32_bf16 v[20:23], v[172:175], v[206:209], v[20:23]
	v_mfma_f32_16x16x32_bf16 v[16:19], v[180:183], v[206:209], v[16:19]
	v_mfma_f32_16x16x32_bf16 v[4:7], v[172:175], v[214:217], v[4:7]
	v_mfma_f32_16x16x32_bf16 v[0:3], v[180:183], v[214:217], v[0:3]
	s_barrier
	s_add_i32 s67, s67, 2
	s_add_u32 s30, s30, 0x100
	s_addc_u32 s31, s31, 0
	s_add_u32 s65, s65, 0x100
	s_addc_u32 s66, s66, 0
	s_cmp_gt_u32 s67, 29
	s_cbranch_scc0 .LBB0_1271
	v_lshl_add_u32 v144, s8, 8, v152
	v_ashrrev_i32_e32 v145, 31, v144
	v_lshl_add_u64 v[150:151], v[144:145], 2, s[16:17]
	global_load_dword v172, v[150:151], off
	global_load_dword v173, v[150:151], off offset:64
	global_load_dword v174, v[150:151], off offset:128
	global_load_dword v175, v[150:151], off offset:192
	global_load_dword v176, v[150:151], off offset:512
	global_load_dword v177, v[150:151], off offset:576
	global_load_dword v178, v[150:151], off offset:640
	global_load_dword v179, v[150:151], off offset:704
	s_and_b64 vcc, exec, s[20:21]
	s_cbranch_vccz .LBB0_1274
	s_barrier

.LBB0_1420:
	s_add_u32 s33, s38, 0xfff80080
	s_addc_u32 s40, s39, -1
	s_cmp_eq_u32 s68, 28
	s_cselect_b32 s43, s27, s40
	s_cselect_b32 s42, s35, s33
	s_cselect_b32 s41, s25, s67
	s_cselect_b32 s40, s65, s66
	v_lshl_add_u64 v[156:157], s[38:39], 0, v[136:137]
	s_add_i32 m0, s37, 0xc000
	s_nop 0
	global_load_lds_dwordx4 v[156:157], off
	v_lshl_add_u64 v[156:157], s[38:39], 0, v[138:139]
	s_add_i32 m0, s37, 0xe000
	s_nop 0
	global_load_lds_dwordx4 v[156:157], off
	ds_read_b128 v[152:155], v161
	ds_read_b128 v[166:169], v161 offset:1024
	ds_read_b128 v[170:173], v161 offset:2048
	ds_read_b128 v[174:177], v161 offset:3072
	ds_read_b128 v[178:181], v162
	ds_read_b128 v[182:185], v162 offset:1024
	ds_read_b128 v[186:189], v162 offset:2048
	ds_read_b128 v[194:197], v162 offset:3072
	ds_read_b128 v[198:201], v163
	ds_read_b128 v[202:205], v163 offset:1024
	ds_read_b128 v[206:209], v163 offset:2048
	ds_read_b128 v[210:213], v163 offset:3072
	ds_read_b128 v[214:217], v163 offset:4096
	ds_read_b128 v[218:221], v163 offset:5120
	ds_read_b128 v[222:225], v163 offset:6144
	ds_read_b128 v[226:229], v163 offset:7168
	s_waitcnt vmcnt(8)
	s_waitcnt lgkmcnt(0)
	s_barrier
	s_waitcnt lgkmcnt(0)
	v_mfma_f32_16x16x32_bf16 v[124:127], v[152:155], v[198:201], v[124:127]
	v_mfma_f32_16x16x32_bf16 v[120:123], v[170:173], v[198:201], v[120:123]
	v_mfma_f32_16x16x32_bf16 v[108:111], v[152:155], v[206:209], v[108:111]
	v_mfma_f32_16x16x32_bf16 v[104:107], v[170:173], v[206:209], v[104:107]
	v_mfma_f32_16x16x32_bf16 v[92:95], v[152:155], v[214:217], v[92:95]
	v_mfma_f32_16x16x32_bf16 v[88:91], v[170:173], v[214:217], v[88:91]
	v_mfma_f32_16x16x32_bf16 v[76:79], v[152:155], v[222:225], v[76:79]
	v_mfma_f32_16x16x32_bf16 v[72:75], v[170:173], v[222:225], v[72:75]
	v_mfma_f32_16x16x32_bf16 v[124:127], v[166:169], v[202:205], v[124:127]
	v_mfma_f32_16x16x32_bf16 v[120:123], v[174:177], v[202:205], v[120:123]
	v_mfma_f32_16x16x32_bf16 v[108:111], v[166:169], v[210:213], v[108:111]
	v_mfma_f32_16x16x32_bf16 v[104:107], v[174:177], v[210:213], v[104:107]
	v_mfma_f32_16x16x32_bf16 v[92:95], v[166:169], v[218:221], v[92:95]
	v_mfma_f32_16x16x32_bf16 v[88:91], v[174:177], v[218:221], v[88:91]
	v_mfma_f32_16x16x32_bf16 v[76:79], v[166:169], v[226:229], v[76:79]
	v_mfma_f32_16x16x32_bf16 v[72:75], v[174:177], v[226:229], v[72:75]
	v_mfma_f32_16x16x32_bf16 v[116:119], v[178:181], v[198:201], v[116:119]
	v_mfma_f32_16x16x32_bf16 v[112:115], v[186:189], v[198:201], v[112:115]
	v_mfma_f32_16x16x32_bf16 v[100:103], v[178:181], v[206:209], v[100:103]
	v_mfma_f32_16x16x32_bf16 v[96:99], v[186:189], v[206:209], v[96:99]
	v_mfma_f32_16x16x32_bf16 v[84:87], v[178:181], v[214:217], v[84:87]
	v_mfma_f32_16x16x32_bf16 v[80:83], v[186:189], v[214:217], v[80:83]
	v_mfma_f32_16x16x32_bf16 v[68:71], v[178:181], v[222:225], v[68:71]
	v_mfma_f32_16x16x32_bf16 v[64:67], v[186:189], v[222:225], v[64:67]
	v_mfma_f32_16x16x32_bf16 v[116:119], v[182:185], v[202:205], v[116:119]
	v_mfma_f32_16x16x32_bf16 v[112:115], v[194:197], v[202:205], v[112:115]
	v_mfma_f32_16x16x32_bf16 v[100:103], v[182:185], v[210:213], v[100:103]
	v_mfma_f32_16x16x32_bf16 v[96:99], v[194:197], v[210:213], v[96:99]
	v_mfma_f32_16x16x32_bf16 v[84:87], v[182:185], v[218:221], v[84:87]
	v_mfma_f32_16x16x32_bf16 v[80:83], v[194:197], v[218:221], v[80:83]
	v_mfma_f32_16x16x32_bf16 v[68:71], v[182:185], v[226:229], v[68:71]
	v_mfma_f32_16x16x32_bf16 v[64:67], v[194:197], v[226:229], v[64:67]
	s_barrier
	s_add_i32 s33, s63, s56
	v_lshl_add_u64 v[156:157], s[40:41], 0, v[130:131]
	s_mov_b32 m0, s33
	s_nop 0
	global_load_lds_dwordx4 v[156:157], off
	s_add_i32 m0, s33, 0x2000
	s_add_u32 s54, s40, 0x80000
	v_lshl_add_u64 v[190:191], s[40:41], 0, v[134:135]
	s_addc_u32 s55, s41, 0
	s_add_i32 s33, s64, s56
	global_load_lds_dwordx4 v[190:191], off
	v_lshl_add_u64 v[230:231], s[54:55], 0, v[130:131]
	s_mov_b32 m0, s33
	v_lshl_add_u64 v[232:233], s[42:43], 0, v[132:133]
	global_load_lds_dwordx4 v[230:231], off
	v_lshl_add_u64 v[230:231], s[54:55], 0, v[134:135]
	s_add_i32 m0, s33, 0x2000
	s_nop 0
	global_load_lds_dwordx4 v[230:231], off
	v_lshl_add_u64 v[230:231], s[42:43], 0, v[128:129]
	s_mov_b32 m0, s37
	s_nop 0
	global_load_lds_dwordx4 v[230:231], off
	s_mov_b32 m0, s57
	s_nop 0
	global_load_lds_dwordx4 v[232:233], off
	ds_read_b128 v[198:201], v163 offset:16384
	ds_read_b128 v[202:205], v163 offset:17408
	ds_read_b128 v[206:209], v163 offset:18432
	ds_read_b128 v[210:213], v163 offset:19456
	ds_read_b128 v[214:217], v163 offset:20480
	ds_read_b128 v[218:221], v163 offset:21504
	ds_read_b128 v[222:225], v163 offset:22528
	ds_read_b128 v[226:229], v163 offset:23552
	s_waitcnt vmcnt(8)
	s_waitcnt lgkmcnt(0)
	s_barrier
	s_waitcnt lgkmcnt(0)
	v_mfma_f32_16x16x32_bf16 v[60:63], v[152:155], v[198:201], v[60:63]
	v_mfma_f32_16x16x32_bf16 v[56:59], v[170:173], v[198:201], v[56:59]
	v_mfma_f32_16x16x32_bf16 v[44:47], v[152:155], v[206:209], v[44:47]
	v_mfma_f32_16x16x32_bf16 v[40:43], v[170:173], v[206:209], v[40:43]
	v_mfma_f32_16x16x32_bf16 v[28:31], v[152:155], v[214:217], v[28:31]
	v_mfma_f32_16x16x32_bf16 v[24:27], v[170:173], v[214:217], v[24:27]
	v_mfma_f32_16x16x32_bf16 v[12:15], v[152:155], v[222:225], v[12:15]
	v_mfma_f32_16x16x32_bf16 v[8:11], v[170:173], v[222:225], v[8:11]
	v_mfma_f32_16x16x32_bf16 v[60:63], v[166:169], v[202:205], v[60:63]
	v_mfma_f32_16x16x32_bf16 v[56:59], v[174:177], v[202:205], v[56:59]
	v_mfma_f32_16x16x32_bf16 v[44:47], v[166:169], v[210:213], v[44:47]
	v_mfma_f32_16x16x32_bf16 v[40:43], v[174:177], v[210:213], v[40:43]
	v_mfma_f32_16x16x32_bf16 v[28:31], v[166:169], v[218:221], v[28:31]
	v_mfma_f32_16x16x32_bf16 v[24:27], v[174:177], v[218:221], v[24:27]
	v_mfma_f32_16x16x32_bf16 v[12:15], v[166:169], v[226:229], v[12:15]
	v_mfma_f32_16x16x32_bf16 v[8:11], v[174:177], v[226:229], v[8:11]
	v_mfma_f32_16x16x32_bf16 v[52:55], v[178:181], v[198:201], v[52:55]
	v_mfma_f32_16x16x32_bf16 v[48:51], v[186:189], v[198:201], v[48:51]
	v_mfma_f32_16x16x32_bf16 v[36:39], v[178:181], v[206:209], v[36:39]
	v_mfma_f32_16x16x32_bf16 v[32:35], v[186:189], v[206:209], v[32:35]
	v_mfma_f32_16x16x32_bf16 v[20:23], v[178:181], v[214:217], v[20:23]
	v_mfma_f32_16x16x32_bf16 v[16:19], v[186:189], v[214:217], v[16:19]
	v_mfma_f32_16x16x32_bf16 v[4:7], v[178:181], v[222:225], v[4:7]
	v_mfma_f32_16x16x32_bf16 v[0:3], v[186:189], v[222:225], v[0:3]
	v_mfma_f32_16x16x32_bf16 v[52:55], v[182:185], v[202:205], v[52:55]
	v_mfma_f32_16x16x32_bf16 v[48:51], v[194:197], v[202:205], v[48:51]
	v_mfma_f32_16x16x32_bf16 v[36:39], v[182:185], v[210:213], v[36:39]
	v_mfma_f32_16x16x32_bf16 v[32:35], v[194:197], v[210:213], v[32:35]
	v_mfma_f32_16x16x32_bf16 v[20:23], v[182:185], v[218:221], v[20:23]
	v_mfma_f32_16x16x32_bf16 v[16:19], v[194:197], v[218:221], v[16:19]
	v_mfma_f32_16x16x32_bf16 v[4:7], v[182:185], v[226:229], v[4:7]
	v_mfma_f32_16x16x32_bf16 v[0:3], v[194:197], v[226:229], v[0:3]
	s_barrier
	s_add_i32 s33, 0, 0x18000
	s_add_i32 s54, 0, 0x1c000
	s_add_u32 s42, s42, 0x80000
	s_addc_u32 s43, s43, 0
	s_mov_b32 m0, s58
	v_lshl_add_u64 v[234:235], s[42:43], 0, v[128:129]
	global_load_lds_dwordx4 v[234:235], off
	v_lshl_add_u64 v[234:235], s[42:43], 0, v[132:133]
	s_mov_b32 m0, s59
	s_nop 0
	global_load_lds_dwordx4 v[234:235], off
	v_add_u32_e32 v165, s33, v159
	ds_read_b128 v[152:155], v165
	ds_read_b128 v[166:169], v165 offset:1024
	ds_read_b128 v[170:173], v165 offset:2048
	ds_read_b128 v[174:177], v165 offset:3072
	v_add_u32_e32 v165, s54, v159
	ds_read_b128 v[178:181], v165
	ds_read_b128 v[182:185], v165 offset:1024
	ds_read_b128 v[186:189], v165 offset:2048
	ds_read_b128 v[194:197], v165 offset:3072
	ds_read_b128 v[198:201], v163 offset:32768
	ds_read_b128 v[202:205], v163 offset:33792
	ds_read_b128 v[206:209], v163 offset:34816
	ds_read_b128 v[210:213], v163 offset:35840
	ds_read_b128 v[214:217], v163 offset:36864
	ds_read_b128 v[218:221], v163 offset:37888
	ds_read_b128 v[222:225], v163 offset:38912
	ds_read_b128 v[226:229], v163 offset:39936
	s_waitcnt vmcnt(8)
	s_waitcnt lgkmcnt(0)
	s_barrier
	s_waitcnt lgkmcnt(0)
	v_mfma_f32_16x16x32_bf16 v[124:127], v[152:155], v[198:201], v[124:127]
	v_mfma_f32_16x16x32_bf16 v[120:123], v[170:173], v[198:201], v[120:123]
	v_mfma_f32_16x16x32_bf16 v[108:111], v[152:155], v[206:209], v[108:111]
	v_mfma_f32_16x16x32_bf16 v[104:107], v[170:173], v[206:209], v[104:107]
	v_mfma_f32_16x16x32_bf16 v[92:95], v[152:155], v[214:217], v[92:95]
	v_mfma_f32_16x16x32_bf16 v[88:91], v[170:173], v[214:217], v[88:91]
	v_mfma_f32_16x16x32_bf16 v[76:79], v[152:155], v[222:225], v[76:79]
	v_mfma_f32_16x16x32_bf16 v[72:75], v[170:173], v[222:225], v[72:75]
	v_mfma_f32_16x16x32_bf16 v[124:127], v[166:169], v[202:205], v[124:127]
	v_mfma_f32_16x16x32_bf16 v[120:123], v[174:177], v[202:205], v[120:123]
	v_mfma_f32_16x16x32_bf16 v[108:111], v[166:169], v[210:213], v[108:111]
	v_mfma_f32_16x16x32_bf16 v[104:107], v[174:177], v[210:213], v[104:107]
	v_mfma_f32_16x16x32_bf16 v[92:95], v[166:169], v[218:221], v[92:95]
	v_mfma_f32_16x16x32_bf16 v[88:91], v[174:177], v[218:221], v[88:91]
	v_mfma_f32_16x16x32_bf16 v[76:79], v[166:169], v[226:229], v[76:79]
	v_mfma_f32_16x16x32_bf16 v[72:75], v[174:177], v[226:229], v[72:75]
	v_mfma_f32_16x16x32_bf16 v[116:119], v[178:181], v[198:201], v[116:119]
	v_mfma_f32_16x16x32_bf16 v[112:115], v[186:189], v[198:201], v[112:115]
	v_mfma_f32_16x16x32_bf16 v[100:103], v[178:181], v[206:209], v[100:103]
	v_mfma_f32_16x16x32_bf16 v[96:99], v[186:189], v[206:209], v[96:99]
	v_mfma_f32_16x16x32_bf16 v[84:87], v[178:181], v[214:217], v[84:87]
	v_mfma_f32_16x16x32_bf16 v[80:83], v[186:189], v[214:217], v[80:83]
	v_mfma_f32_16x16x32_bf16 v[68:71], v[178:181], v[222:225], v[68:71]
	v_mfma_f32_16x16x32_bf16 v[64:67], v[186:189], v[222:225], v[64:67]
	v_mfma_f32_16x16x32_bf16 v[116:119], v[182:185], v[202:205], v[116:119]
	v_mfma_f32_16x16x32_bf16 v[112:115], v[194:197], v[202:205], v[112:115]
	v_mfma_f32_16x16x32_bf16 v[100:103], v[182:185], v[210:213], v[100:103]
	v_mfma_f32_16x16x32_bf16 v[96:99], v[194:197], v[210:213], v[96:99]
	v_mfma_f32_16x16x32_bf16 v[84:87], v[182:185], v[218:221], v[84:87]
	v_mfma_f32_16x16x32_bf16 v[80:83], v[194:197], v[218:221], v[80:83]
	v_mfma_f32_16x16x32_bf16 v[68:71], v[182:185], v[226:229], v[68:71]
	v_mfma_f32_16x16x32_bf16 v[64:67], v[194:197], v[226:229], v[64:67]
	s_barrier
	s_add_i32 s33, s33, s56
	v_lshl_add_u64 v[156:157], v[156:157], 0, s[20:21]
	s_mov_b32 m0, s33
	s_nop 0
	global_load_lds_dwordx4 v[156:157], off
	s_add_i32 m0, s33, 0x2000
	s_add_u32 s40, s40, 0x80080
	v_lshl_add_u64 v[156:157], v[190:191], 0, s[20:21]
	s_addc_u32 s41, s41, 0
	s_add_i32 s33, s54, s56
	global_load_lds_dwordx4 v[156:157], off
	v_lshl_add_u64 v[156:157], s[40:41], 0, v[130:131]
	s_mov_b32 m0, s33
	s_nop 0
	global_load_lds_dwordx4 v[156:157], off
	v_lshl_add_u64 v[156:157], s[40:41], 0, v[134:135]
	s_add_i32 m0, s33, 0x2000
	s_nop 0
	global_load_lds_dwordx4 v[156:157], off
	v_lshl_add_u64 v[156:157], v[230:231], 0, s[20:21]
	s_mov_b32 m0, s61
	s_nop 0
	global_load_lds_dwordx4 v[156:157], off
	v_lshl_add_u64 v[156:157], v[232:233], 0, s[20:21]
	s_mov_b32 m0, s62
	s_nop 0
	global_load_lds_dwordx4 v[156:157], off
	ds_read_b128 v[198:201], v163 offset:49152
	ds_read_b128 v[202:205], v163 offset:50176
	ds_read_b128 v[206:209], v163 offset:51200
	ds_read_b128 v[210:213], v163 offset:52224
	ds_read_b128 v[214:217], v163 offset:53248
	ds_read_b128 v[218:221], v163 offset:54272
	ds_read_b128 v[222:225], v163 offset:55296
	ds_read_b128 v[226:229], v163 offset:56320
	s_waitcnt vmcnt(8)
	s_waitcnt lgkmcnt(0)
	s_barrier
	s_waitcnt lgkmcnt(0)
	v_mfma_f32_16x16x32_bf16 v[60:63], v[152:155], v[198:201], v[60:63]
	v_mfma_f32_16x16x32_bf16 v[56:59], v[170:173], v[198:201], v[56:59]
	v_mfma_f32_16x16x32_bf16 v[44:47], v[152:155], v[206:209], v[44:47]
	v_mfma_f32_16x16x32_bf16 v[40:43], v[170:173], v[206:209], v[40:43]
	v_mfma_f32_16x16x32_bf16 v[28:31], v[152:155], v[214:217], v[28:31]
	v_mfma_f32_16x16x32_bf16 v[24:27], v[170:173], v[214:217], v[24:27]
	v_mfma_f32_16x16x32_bf16 v[12:15], v[152:155], v[222:225], v[12:15]
	v_mfma_f32_16x16x32_bf16 v[8:11], v[170:173], v[222:225], v[8:11]
	v_mfma_f32_16x16x32_bf16 v[60:63], v[166:169], v[202:205], v[60:63]
	v_mfma_f32_16x16x32_bf16 v[56:59], v[174:177], v[202:205], v[56:59]
	v_mfma_f32_16x16x32_bf16 v[44:47], v[166:169], v[210:213], v[44:47]
	v_mfma_f32_16x16x32_bf16 v[40:43], v[174:177], v[210:213], v[40:43]
	v_mfma_f32_16x16x32_bf16 v[28:31], v[166:169], v[218:221], v[28:31]
	v_mfma_f32_16x16x32_bf16 v[24:27], v[174:177], v[218:221], v[24:27]
	v_mfma_f32_16x16x32_bf16 v[12:15], v[166:169], v[226:229], v[12:15]
	v_mfma_f32_16x16x32_bf16 v[8:11], v[174:177], v[226:229], v[8:11]
	v_mfma_f32_16x16x32_bf16 v[52:55], v[178:181], v[198:201], v[52:55]
	v_mfma_f32_16x16x32_bf16 v[48:51], v[186:189], v[198:201], v[48:51]
	v_mfma_f32_16x16x32_bf16 v[36:39], v[178:181], v[206:209], v[36:39]
	v_mfma_f32_16x16x32_bf16 v[32:35], v[186:189], v[206:209], v[32:35]
	v_mfma_f32_16x16x32_bf16 v[20:23], v[178:181], v[214:217], v[20:23]
	v_mfma_f32_16x16x32_bf16 v[16:19], v[186:189], v[214:217], v[16:19]
	v_mfma_f32_16x16x32_bf16 v[4:7], v[178:181], v[222:225], v[4:7]
	v_mfma_f32_16x16x32_bf16 v[0:3], v[186:189], v[222:225], v[0:3]
	v_mfma_f32_16x16x32_bf16 v[52:55], v[182:185], v[202:205], v[52:55]
	v_mfma_f32_16x16x32_bf16 v[48:51], v[194:197], v[202:205], v[48:51]
	v_mfma_f32_16x16x32_bf16 v[36:39], v[182:185], v[210:213], v[36:39]
	v_mfma_f32_16x16x32_bf16 v[32:35], v[194:197], v[210:213], v[32:35]
	v_mfma_f32_16x16x32_bf16 v[20:23], v[182:185], v[218:221], v[20:23]
	v_mfma_f32_16x16x32_bf16 v[16:19], v[194:197], v[218:221], v[16:19]
	v_mfma_f32_16x16x32_bf16 v[4:7], v[182:185], v[226:229], v[4:7]
	v_mfma_f32_16x16x32_bf16 v[0:3], v[194:197], v[226:229], v[0:3]
	s_barrier
	s_add_i32 s68, s68, 2
	s_add_u32 s38, s38, 0x100
	s_addc_u32 s39, s39, 0
	s_add_u32 s66, s66, 0x100
	s_addc_u32 s67, s67, 0
	s_cmp_gt_u32 s68, 29
	s_cbranch_scc0 .LBB0_1420
	v_lshl_add_u32 v156, s34, 8, v158
	v_lshl_or_b32 v154, s36, 8, v160
	v_ashrrev_i32_e32 v157, 31, v156
	v_ashrrev_i32_e32 v155, 31, v154
	v_lshlrev_b64 v[152:153], 11, v[156:157]
	v_lshl_add_u64 v[152:153], v[152:153], 0, v[154:155]
	v_lshlrev_b64 v[170:171], 1, v[152:153]
	v_lshl_add_u64 v[172:173], s[12:13], 0, v[170:171]
	global_load_dwordx4 v[180:183], v[172:173], off
	global_load_dwordx4 v[184:187], v[172:173], off offset:256
	v_add_co_u32_e32 v252, vcc, 0x10000, v172
	s_nop 1
	v_addc_co_u32_e32 v253, vcc, 0, v173, vcc
	global_load_dwordx4 v[188:191], v[252:253], off
	global_load_dwordx4 v[194:197], v[252:253], off offset:256
	v_add_co_u32_e32 v254, vcc, 0x20000, v172
	s_nop 1
	v_addc_co_u32_e32 v255, vcc, 0, v173, vcc
	global_load_dwordx4 v[198:201], v[254:255], off
	global_load_dwordx4 v[202:205], v[254:255], off offset:256
	v_add_co_u32_e32 v252, vcc, 0x30000, v172
	s_nop 1
	v_addc_co_u32_e32 v253, vcc, 0, v173, vcc
	global_load_dwordx4 v[206:209], v[252:253], off
	global_load_dwordx4 v[210:213], v[252:253], off offset:256
	v_add_co_u32_e32 v254, vcc, 0x80000, v172
	s_nop 1
	v_addc_co_u32_e32 v255, vcc, 0, v173, vcc
	global_load_dwordx4 v[214:217], v[254:255], off
	global_load_dwordx4 v[218:221], v[254:255], off offset:256
	v_add_co_u32_e32 v252, vcc, 0x90000, v172
	s_nop 1
	v_addc_co_u32_e32 v253, vcc, 0, v173, vcc
	global_load_dwordx4 v[222:225], v[252:253], off
	global_load_dwordx4 v[226:229], v[252:253], off offset:256
	v_add_co_u32_e32 v254, vcc, 0xa0000, v172
	s_nop 1
	v_addc_co_u32_e32 v255, vcc, 0, v173, vcc
	global_load_dwordx4 v[230:233], v[254:255], off
	global_load_dwordx4 v[234:237], v[254:255], off offset:256
	v_add_co_u32_e32 v252, vcc, 0xb0000, v172
	s_nop 1
	v_addc_co_u32_e32 v253, vcc, 0, v173, vcc
	global_load_dwordx4 v[238:241], v[252:253], off
	global_load_dwordx4 v[242:245], v[252:253], off offset:256
	s_and_b64 vcc, exec, s[22:23]
	s_cbranch_vccz .LBB0_1423
	s_barrier

.LBB0_1504:
	s_add_u32 s30, s28, 0xfff80080
	s_addc_u32 s31, s29, -1
	s_cmp_eq_u32 s65, 28
	s_cselect_b32 s35, s23, s31
	s_cselect_b32 s34, s61, s30
	s_cselect_b32 s31, s21, s64
	s_cselect_b32 s30, s62, s63
	v_lshl_add_u64 v[148:149], s[28:29], 0, v[136:137]
	s_add_i32 m0, s42, 0xc000
	s_nop 0
	global_load_lds_dwordx4 v[148:149], off
	v_lshl_add_u64 v[148:149], s[28:29], 0, v[138:139]
	s_add_i32 m0, s42, 0xe000
	s_nop 0
	global_load_lds_dwordx4 v[148:149], off
	ds_read_b128 v[144:147], v153
	ds_read_b128 v[158:161], v153 offset:1024
	ds_read_b128 v[162:165], v153 offset:2048
	ds_read_b128 v[166:169], v153 offset:3072
	ds_read_b128 v[170:173], v154
	ds_read_b128 v[174:177], v154 offset:1024
	ds_read_b128 v[178:181], v154 offset:2048
	ds_read_b128 v[182:185], v154 offset:3072
	ds_read_b128 v[186:189], v155
	ds_read_b128 v[194:197], v155 offset:1024
	ds_read_b128 v[198:201], v155 offset:2048
	ds_read_b128 v[202:205], v155 offset:3072
	ds_read_b128 v[206:209], v155 offset:4096
	ds_read_b128 v[210:213], v155 offset:5120
	ds_read_b128 v[214:217], v155 offset:6144
	ds_read_b128 v[218:221], v155 offset:7168
	s_waitcnt vmcnt(8)
	s_waitcnt lgkmcnt(0)
	s_barrier
	s_waitcnt lgkmcnt(0)
	v_mfma_f32_16x16x32_bf16 v[116:119], v[144:147], v[186:189], v[116:119]
	v_mfma_f32_16x16x32_bf16 v[112:115], v[162:165], v[186:189], v[112:115]
	v_mfma_f32_16x16x32_bf16 v[100:103], v[144:147], v[198:201], v[100:103]
	v_mfma_f32_16x16x32_bf16 v[96:99], v[162:165], v[198:201], v[96:99]
	v_mfma_f32_16x16x32_bf16 v[84:87], v[144:147], v[206:209], v[84:87]
	v_mfma_f32_16x16x32_bf16 v[80:83], v[162:165], v[206:209], v[80:83]
	v_mfma_f32_16x16x32_bf16 v[68:71], v[144:147], v[214:217], v[68:71]
	v_mfma_f32_16x16x32_bf16 v[64:67], v[162:165], v[214:217], v[64:67]
	v_mfma_f32_16x16x32_bf16 v[116:119], v[158:161], v[194:197], v[116:119]
	v_mfma_f32_16x16x32_bf16 v[112:115], v[166:169], v[194:197], v[112:115]
	v_mfma_f32_16x16x32_bf16 v[100:103], v[158:161], v[202:205], v[100:103]
	v_mfma_f32_16x16x32_bf16 v[96:99], v[166:169], v[202:205], v[96:99]
	v_mfma_f32_16x16x32_bf16 v[84:87], v[158:161], v[210:213], v[84:87]
	v_mfma_f32_16x16x32_bf16 v[80:83], v[166:169], v[210:213], v[80:83]
	v_mfma_f32_16x16x32_bf16 v[68:71], v[158:161], v[218:221], v[68:71]
	v_mfma_f32_16x16x32_bf16 v[64:67], v[166:169], v[218:221], v[64:67]
	v_mfma_f32_16x16x32_bf16 v[124:127], v[170:173], v[186:189], v[124:127]
	v_mfma_f32_16x16x32_bf16 v[120:123], v[178:181], v[186:189], v[120:123]
	v_mfma_f32_16x16x32_bf16 v[108:111], v[170:173], v[198:201], v[108:111]
	v_mfma_f32_16x16x32_bf16 v[104:107], v[178:181], v[198:201], v[104:107]
	v_mfma_f32_16x16x32_bf16 v[92:95], v[170:173], v[206:209], v[92:95]
	v_mfma_f32_16x16x32_bf16 v[88:91], v[178:181], v[206:209], v[88:91]
	v_mfma_f32_16x16x32_bf16 v[76:79], v[170:173], v[214:217], v[76:79]
	v_mfma_f32_16x16x32_bf16 v[72:75], v[178:181], v[214:217], v[72:75]
	v_mfma_f32_16x16x32_bf16 v[124:127], v[174:177], v[194:197], v[124:127]
	v_mfma_f32_16x16x32_bf16 v[120:123], v[182:185], v[194:197], v[120:123]
	v_mfma_f32_16x16x32_bf16 v[108:111], v[174:177], v[202:205], v[108:111]
	v_mfma_f32_16x16x32_bf16 v[104:107], v[182:185], v[202:205], v[104:107]
	v_mfma_f32_16x16x32_bf16 v[92:95], v[174:177], v[210:213], v[92:95]
	v_mfma_f32_16x16x32_bf16 v[88:91], v[182:185], v[210:213], v[88:91]
	v_mfma_f32_16x16x32_bf16 v[76:79], v[174:177], v[218:221], v[76:79]
	v_mfma_f32_16x16x32_bf16 v[72:75], v[182:185], v[218:221], v[72:75]
	s_barrier
	s_add_i32 s33, s57, s40
	v_lshl_add_u64 v[148:149], s[30:31], 0, v[132:133]
	s_mov_b32 m0, s33
	s_nop 0
	global_load_lds_dwordx4 v[148:149], off
	s_add_i32 m0, s33, 0x2000
	s_add_u32 s54, s30, 0x80000
	v_lshl_add_u64 v[190:191], s[30:31], 0, v[128:129]
	s_addc_u32 s55, s31, 0
	s_add_i32 s33, s58, s40
	global_load_lds_dwordx4 v[190:191], off
	v_lshl_add_u64 v[222:223], s[54:55], 0, v[132:133]
	s_mov_b32 m0, s33
	v_lshl_add_u64 v[224:225], s[34:35], 0, v[130:131]
	global_load_lds_dwordx4 v[222:223], off
	v_lshl_add_u64 v[222:223], s[54:55], 0, v[128:129]
	s_add_i32 m0, s33, 0x2000
	s_nop 0
	global_load_lds_dwordx4 v[222:223], off
	v_lshl_add_u64 v[222:223], s[34:35], 0, v[134:135]
	s_mov_b32 m0, s42
	s_nop 0
	global_load_lds_dwordx4 v[222:223], off
	s_mov_b32 m0, s43
	s_nop 0
	global_load_lds_dwordx4 v[224:225], off
	ds_read_b128 v[186:189], v155 offset:16384
	ds_read_b128 v[194:197], v155 offset:17408
	ds_read_b128 v[198:201], v155 offset:18432
	ds_read_b128 v[202:205], v155 offset:19456
	ds_read_b128 v[206:209], v155 offset:20480
	ds_read_b128 v[210:213], v155 offset:21504
	ds_read_b128 v[214:217], v155 offset:22528
	ds_read_b128 v[218:221], v155 offset:23552
	s_waitcnt vmcnt(8)
	s_waitcnt lgkmcnt(0)
	s_barrier
	s_waitcnt lgkmcnt(0)
	v_mfma_f32_16x16x32_bf16 v[52:55], v[144:147], v[186:189], v[52:55]
	v_mfma_f32_16x16x32_bf16 v[48:51], v[162:165], v[186:189], v[48:51]
	v_mfma_f32_16x16x32_bf16 v[36:39], v[144:147], v[198:201], v[36:39]
	v_mfma_f32_16x16x32_bf16 v[32:35], v[162:165], v[198:201], v[32:35]
	v_mfma_f32_16x16x32_bf16 v[20:23], v[144:147], v[206:209], v[20:23]
	v_mfma_f32_16x16x32_bf16 v[16:19], v[162:165], v[206:209], v[16:19]
	v_mfma_f32_16x16x32_bf16 v[4:7], v[144:147], v[214:217], v[4:7]
	v_mfma_f32_16x16x32_bf16 v[0:3], v[162:165], v[214:217], v[0:3]
	v_mfma_f32_16x16x32_bf16 v[52:55], v[158:161], v[194:197], v[52:55]
	v_mfma_f32_16x16x32_bf16 v[48:51], v[166:169], v[194:197], v[48:51]
	v_mfma_f32_16x16x32_bf16 v[36:39], v[158:161], v[202:205], v[36:39]
	v_mfma_f32_16x16x32_bf16 v[32:35], v[166:169], v[202:205], v[32:35]
	v_mfma_f32_16x16x32_bf16 v[20:23], v[158:161], v[210:213], v[20:23]
	v_mfma_f32_16x16x32_bf16 v[16:19], v[166:169], v[210:213], v[16:19]
	v_mfma_f32_16x16x32_bf16 v[4:7], v[158:161], v[218:221], v[4:7]
	v_mfma_f32_16x16x32_bf16 v[0:3], v[166:169], v[218:221], v[0:3]
	v_mfma_f32_16x16x32_bf16 v[60:63], v[170:173], v[186:189], v[60:63]
	v_mfma_f32_16x16x32_bf16 v[56:59], v[178:181], v[186:189], v[56:59]
	v_mfma_f32_16x16x32_bf16 v[44:47], v[170:173], v[198:201], v[44:47]
	v_mfma_f32_16x16x32_bf16 v[40:43], v[178:181], v[198:201], v[40:43]
	v_mfma_f32_16x16x32_bf16 v[28:31], v[170:173], v[206:209], v[28:31]
	v_mfma_f32_16x16x32_bf16 v[24:27], v[178:181], v[206:209], v[24:27]
	v_mfma_f32_16x16x32_bf16 v[12:15], v[170:173], v[214:217], v[12:15]
	v_mfma_f32_16x16x32_bf16 v[8:11], v[178:181], v[214:217], v[8:11]
	v_mfma_f32_16x16x32_bf16 v[60:63], v[174:177], v[194:197], v[60:63]
	v_mfma_f32_16x16x32_bf16 v[56:59], v[182:185], v[194:197], v[56:59]
	v_mfma_f32_16x16x32_bf16 v[44:47], v[174:177], v[202:205], v[44:47]
	v_mfma_f32_16x16x32_bf16 v[40:43], v[182:185], v[202:205], v[40:43]
	v_mfma_f32_16x16x32_bf16 v[28:31], v[174:177], v[210:213], v[28:31]
	v_mfma_f32_16x16x32_bf16 v[24:27], v[182:185], v[210:213], v[24:27]
	v_mfma_f32_16x16x32_bf16 v[12:15], v[174:177], v[218:221], v[12:15]
	v_mfma_f32_16x16x32_bf16 v[8:11], v[182:185], v[218:221], v[8:11]
	s_barrier
	s_add_i32 s33, 0, 0x18000
	s_add_i32 s54, 0, 0x1c000
	s_add_u32 s34, s34, 0x80000
	s_addc_u32 s35, s35, 0
	s_mov_b32 m0, s48
	v_lshl_add_u64 v[226:227], s[34:35], 0, v[134:135]
	global_load_lds_dwordx4 v[226:227], off
	v_lshl_add_u64 v[226:227], s[34:35], 0, v[130:131]
	s_mov_b32 m0, s49
	s_nop 0
	global_load_lds_dwordx4 v[226:227], off
	v_add_u32_e32 v166, s33, v151
	v_add_u32_e32 v182, s54, v151
	ds_read_b128 v[144:147], v166
	ds_read_b128 v[158:161], v166 offset:1024
	ds_read_b128 v[162:165], v166 offset:2048
	ds_read_b128 v[166:169], v166 offset:3072
	ds_read_b128 v[170:173], v182
	ds_read_b128 v[174:177], v182 offset:1024
	ds_read_b128 v[178:181], v182 offset:2048
	ds_read_b128 v[182:185], v182 offset:3072
	ds_read_b128 v[186:189], v155 offset:32768
	ds_read_b128 v[194:197], v155 offset:33792
	ds_read_b128 v[198:201], v155 offset:34816
	ds_read_b128 v[202:205], v155 offset:35840
	ds_read_b128 v[206:209], v155 offset:36864
	ds_read_b128 v[210:213], v155 offset:37888
	ds_read_b128 v[214:217], v155 offset:38912
	ds_read_b128 v[218:221], v155 offset:39936
	s_waitcnt vmcnt(8)
	s_waitcnt lgkmcnt(0)
	s_barrier
	s_waitcnt lgkmcnt(0)
	v_mfma_f32_16x16x32_bf16 v[116:119], v[144:147], v[186:189], v[116:119]
	v_mfma_f32_16x16x32_bf16 v[112:115], v[162:165], v[186:189], v[112:115]
	v_mfma_f32_16x16x32_bf16 v[100:103], v[144:147], v[198:201], v[100:103]
	v_mfma_f32_16x16x32_bf16 v[96:99], v[162:165], v[198:201], v[96:99]
	v_mfma_f32_16x16x32_bf16 v[84:87], v[144:147], v[206:209], v[84:87]
	v_mfma_f32_16x16x32_bf16 v[80:83], v[162:165], v[206:209], v[80:83]
	v_mfma_f32_16x16x32_bf16 v[68:71], v[144:147], v[214:217], v[68:71]
	v_mfma_f32_16x16x32_bf16 v[64:67], v[162:165], v[214:217], v[64:67]
	v_mfma_f32_16x16x32_bf16 v[116:119], v[158:161], v[194:197], v[116:119]
	v_mfma_f32_16x16x32_bf16 v[112:115], v[166:169], v[194:197], v[112:115]
	v_mfma_f32_16x16x32_bf16 v[100:103], v[158:161], v[202:205], v[100:103]
	v_mfma_f32_16x16x32_bf16 v[96:99], v[166:169], v[202:205], v[96:99]
	v_mfma_f32_16x16x32_bf16 v[84:87], v[158:161], v[210:213], v[84:87]
	v_mfma_f32_16x16x32_bf16 v[80:83], v[166:169], v[210:213], v[80:83]
	v_mfma_f32_16x16x32_bf16 v[68:71], v[158:161], v[218:221], v[68:71]
	v_mfma_f32_16x16x32_bf16 v[64:67], v[166:169], v[218:221], v[64:67]
	v_mfma_f32_16x16x32_bf16 v[124:127], v[170:173], v[186:189], v[124:127]
	v_mfma_f32_16x16x32_bf16 v[120:123], v[178:181], v[186:189], v[120:123]
	v_mfma_f32_16x16x32_bf16 v[108:111], v[170:173], v[198:201], v[108:111]
	v_mfma_f32_16x16x32_bf16 v[104:107], v[178:181], v[198:201], v[104:107]
	v_mfma_f32_16x16x32_bf16 v[92:95], v[170:173], v[206:209], v[92:95]
	v_mfma_f32_16x16x32_bf16 v[88:91], v[178:181], v[206:209], v[88:91]
	v_mfma_f32_16x16x32_bf16 v[76:79], v[170:173], v[214:217], v[76:79]
	v_mfma_f32_16x16x32_bf16 v[72:75], v[178:181], v[214:217], v[72:75]
	v_mfma_f32_16x16x32_bf16 v[124:127], v[174:177], v[194:197], v[124:127]
	v_mfma_f32_16x16x32_bf16 v[120:123], v[182:185], v[194:197], v[120:123]
	v_mfma_f32_16x16x32_bf16 v[108:111], v[174:177], v[202:205], v[108:111]
	v_mfma_f32_16x16x32_bf16 v[104:107], v[182:185], v[202:205], v[104:107]
	v_mfma_f32_16x16x32_bf16 v[92:95], v[174:177], v[210:213], v[92:95]
	v_mfma_f32_16x16x32_bf16 v[88:91], v[182:185], v[210:213], v[88:91]
	v_mfma_f32_16x16x32_bf16 v[76:79], v[174:177], v[218:221], v[76:79]
	v_mfma_f32_16x16x32_bf16 v[72:75], v[182:185], v[218:221], v[72:75]
	s_barrier
	s_add_i32 s33, s33, s40
	v_lshl_add_u64 v[148:149], v[148:149], 0, s[16:17]
	s_mov_b32 m0, s33
	s_nop 0
	global_load_lds_dwordx4 v[148:149], off
	s_add_i32 m0, s33, 0x2000
	s_add_u32 s30, s30, 0x80080
	v_lshl_add_u64 v[148:149], v[190:191], 0, s[16:17]
	s_addc_u32 s31, s31, 0
	s_add_i32 s33, s54, s40
	global_load_lds_dwordx4 v[148:149], off
	v_lshl_add_u64 v[148:149], s[30:31], 0, v[132:133]
	s_mov_b32 m0, s33
	s_nop 0
	global_load_lds_dwordx4 v[148:149], off
	v_lshl_add_u64 v[148:149], s[30:31], 0, v[128:129]
	s_add_i32 m0, s33, 0x2000
	s_nop 0
	global_load_lds_dwordx4 v[148:149], off
	v_lshl_add_u64 v[148:149], v[222:223], 0, s[16:17]
	s_mov_b32 m0, s51
	s_nop 0
	global_load_lds_dwordx4 v[148:149], off
	v_lshl_add_u64 v[148:149], v[224:225], 0, s[16:17]
	s_mov_b32 m0, s56
	s_nop 0
	global_load_lds_dwordx4 v[148:149], off
	ds_read_b128 v[186:189], v155 offset:49152
	ds_read_b128 v[194:197], v155 offset:50176
	ds_read_b128 v[198:201], v155 offset:51200
	ds_read_b128 v[202:205], v155 offset:52224
	ds_read_b128 v[206:209], v155 offset:53248
	ds_read_b128 v[210:213], v155 offset:54272
	ds_read_b128 v[214:217], v155 offset:55296
	ds_read_b128 v[218:221], v155 offset:56320
	s_waitcnt vmcnt(8)
	s_waitcnt lgkmcnt(0)
	s_barrier
	s_waitcnt lgkmcnt(0)
	v_mfma_f32_16x16x32_bf16 v[52:55], v[144:147], v[186:189], v[52:55]
	v_mfma_f32_16x16x32_bf16 v[48:51], v[162:165], v[186:189], v[48:51]
	v_mfma_f32_16x16x32_bf16 v[36:39], v[144:147], v[198:201], v[36:39]
	v_mfma_f32_16x16x32_bf16 v[32:35], v[162:165], v[198:201], v[32:35]
	v_mfma_f32_16x16x32_bf16 v[20:23], v[144:147], v[206:209], v[20:23]
	v_mfma_f32_16x16x32_bf16 v[16:19], v[162:165], v[206:209], v[16:19]
	v_mfma_f32_16x16x32_bf16 v[4:7], v[144:147], v[214:217], v[4:7]
	v_mfma_f32_16x16x32_bf16 v[0:3], v[162:165], v[214:217], v[0:3]
	v_mfma_f32_16x16x32_bf16 v[52:55], v[158:161], v[194:197], v[52:55]
	v_mfma_f32_16x16x32_bf16 v[48:51], v[166:169], v[194:197], v[48:51]
	v_mfma_f32_16x16x32_bf16 v[36:39], v[158:161], v[202:205], v[36:39]
	v_mfma_f32_16x16x32_bf16 v[32:35], v[166:169], v[202:205], v[32:35]
	v_mfma_f32_16x16x32_bf16 v[20:23], v[158:161], v[210:213], v[20:23]
	v_mfma_f32_16x16x32_bf16 v[16:19], v[166:169], v[210:213], v[16:19]
	v_mfma_f32_16x16x32_bf16 v[4:7], v[158:161], v[218:221], v[4:7]
	v_mfma_f32_16x16x32_bf16 v[0:3], v[166:169], v[218:221], v[0:3]
	v_mfma_f32_16x16x32_bf16 v[60:63], v[170:173], v[186:189], v[60:63]
	v_mfma_f32_16x16x32_bf16 v[56:59], v[178:181], v[186:189], v[56:59]
	v_mfma_f32_16x16x32_bf16 v[44:47], v[170:173], v[198:201], v[44:47]
	v_mfma_f32_16x16x32_bf16 v[40:43], v[178:181], v[198:201], v[40:43]
	v_mfma_f32_16x16x32_bf16 v[28:31], v[170:173], v[206:209], v[28:31]
	v_mfma_f32_16x16x32_bf16 v[24:27], v[178:181], v[206:209], v[24:27]
	v_mfma_f32_16x16x32_bf16 v[12:15], v[170:173], v[214:217], v[12:15]
	v_mfma_f32_16x16x32_bf16 v[8:11], v[178:181], v[214:217], v[8:11]
	v_mfma_f32_16x16x32_bf16 v[60:63], v[174:177], v[194:197], v[60:63]
	v_mfma_f32_16x16x32_bf16 v[56:59], v[182:185], v[194:197], v[56:59]
	v_mfma_f32_16x16x32_bf16 v[44:47], v[174:177], v[202:205], v[44:47]
	v_mfma_f32_16x16x32_bf16 v[40:43], v[182:185], v[202:205], v[40:43]
	v_mfma_f32_16x16x32_bf16 v[28:31], v[174:177], v[210:213], v[28:31]
	v_mfma_f32_16x16x32_bf16 v[24:27], v[182:185], v[210:213], v[24:27]
	v_mfma_f32_16x16x32_bf16 v[12:15], v[174:177], v[218:221], v[12:15]
	v_mfma_f32_16x16x32_bf16 v[8:11], v[182:185], v[218:221], v[8:11]
	s_barrier
	s_add_i32 s65, s65, 2
	s_add_u32 s28, s28, 0x100
	s_addc_u32 s29, s29, 0
	s_add_u32 s63, s63, 0x100
	s_addc_u32 s64, s64, 0
	s_cmp_gt_u32 s65, 29
	s_cbranch_scc0 .LBB0_1504
	v_lshl_add_u32 v144, s8, 8, v150
	v_ashrrev_i32_e32 v145, 31, v144
	v_lshl_add_u64 v[148:149], v[144:145], 2, s[14:15]
	global_load_dword v172, v[148:149], off
	global_load_dword v173, v[148:149], off offset:64
	global_load_dword v174, v[148:149], off offset:128
	global_load_dword v175, v[148:149], off offset:192
	global_load_dword v176, v[148:149], off offset:512
	global_load_dword v177, v[148:149], off offset:576
	global_load_dword v178, v[148:149], off offset:640
	global_load_dword v179, v[148:149], off offset:704
	s_and_b64 vcc, exec, s[18:19]
	s_cbranch_vccz .LBB0_1507
	s_barrier

.LBB0_2011:
	s_add_u32 s36, s34, 0x100
	s_addc_u32 s37, s35, 0
	s_cmpk_eq_i32 s68, 0x54
	s_cselect_b32 s41, s11, s37
	s_cselect_b32 s40, s10, s36
	s_cselect_b32 s39, s31, s67
	s_cselect_b32 s38, s30, s66
	v_lshl_add_u64 v[148:149], s[34:35], 0, v[136:137]
	s_add_i32 m0, s51, 0xc000
	s_nop 0
	global_load_lds_dwordx4 v[148:149], off
	v_lshl_add_u64 v[148:149], s[34:35], 0, v[138:139]
	s_add_i32 m0, s51, 0xe000
	s_nop 0
	global_load_lds_dwordx4 v[148:149], off
	ds_read_b128 v[144:147], v153
	ds_read_b128 v[158:161], v153 offset:1024
	ds_read_b128 v[162:165], v153 offset:2048
	ds_read_b128 v[166:169], v153 offset:3072
	ds_read_b128 v[170:173], v154
	ds_read_b128 v[174:177], v154 offset:1024
	ds_read_b128 v[178:181], v154 offset:2048
	ds_read_b128 v[182:185], v154 offset:3072
	ds_read_b128 v[186:189], v155
	ds_read_b128 v[194:197], v155 offset:1024
	ds_read_b128 v[198:201], v155 offset:2048
	ds_read_b128 v[202:205], v155 offset:3072
	ds_read_b128 v[206:209], v155 offset:4096
	ds_read_b128 v[210:213], v155 offset:5120
	ds_read_b128 v[214:217], v155 offset:6144
	ds_read_b128 v[218:221], v155 offset:7168
	s_waitcnt vmcnt(8)
	s_waitcnt lgkmcnt(0)
	s_barrier
	s_waitcnt lgkmcnt(0)
	v_mfma_f32_16x16x32_bf16 v[124:127], v[144:147], v[186:189], v[124:127]
	v_mfma_f32_16x16x32_bf16 v[120:123], v[162:165], v[186:189], v[120:123]
	v_mfma_f32_16x16x32_bf16 v[108:111], v[144:147], v[198:201], v[108:111]
	v_mfma_f32_16x16x32_bf16 v[104:107], v[162:165], v[198:201], v[104:107]
	v_mfma_f32_16x16x32_bf16 v[92:95], v[144:147], v[206:209], v[92:95]
	v_mfma_f32_16x16x32_bf16 v[88:91], v[162:165], v[206:209], v[88:91]
	v_mfma_f32_16x16x32_bf16 v[76:79], v[144:147], v[214:217], v[76:79]
	v_mfma_f32_16x16x32_bf16 v[72:75], v[162:165], v[214:217], v[72:75]
	v_mfma_f32_16x16x32_bf16 v[124:127], v[158:161], v[194:197], v[124:127]
	v_mfma_f32_16x16x32_bf16 v[120:123], v[166:169], v[194:197], v[120:123]
	v_mfma_f32_16x16x32_bf16 v[108:111], v[158:161], v[202:205], v[108:111]
	v_mfma_f32_16x16x32_bf16 v[104:107], v[166:169], v[202:205], v[104:107]
	v_mfma_f32_16x16x32_bf16 v[92:95], v[158:161], v[210:213], v[92:95]
	v_mfma_f32_16x16x32_bf16 v[88:91], v[166:169], v[210:213], v[88:91]
	v_mfma_f32_16x16x32_bf16 v[76:79], v[158:161], v[218:221], v[76:79]
	v_mfma_f32_16x16x32_bf16 v[72:75], v[166:169], v[218:221], v[72:75]
	v_mfma_f32_16x16x32_bf16 v[116:119], v[170:173], v[186:189], v[116:119]
	v_mfma_f32_16x16x32_bf16 v[112:115], v[178:181], v[186:189], v[112:115]
	v_mfma_f32_16x16x32_bf16 v[100:103], v[170:173], v[198:201], v[100:103]
	v_mfma_f32_16x16x32_bf16 v[96:99], v[178:181], v[198:201], v[96:99]
	v_mfma_f32_16x16x32_bf16 v[84:87], v[170:173], v[206:209], v[84:87]
	v_mfma_f32_16x16x32_bf16 v[80:83], v[178:181], v[206:209], v[80:83]
	v_mfma_f32_16x16x32_bf16 v[68:71], v[170:173], v[214:217], v[68:71]
	v_mfma_f32_16x16x32_bf16 v[64:67], v[178:181], v[214:217], v[64:67]
	v_mfma_f32_16x16x32_bf16 v[116:119], v[174:177], v[194:197], v[116:119]
	v_mfma_f32_16x16x32_bf16 v[112:115], v[182:185], v[194:197], v[112:115]
	v_mfma_f32_16x16x32_bf16 v[100:103], v[174:177], v[202:205], v[100:103]
	v_mfma_f32_16x16x32_bf16 v[96:99], v[182:185], v[202:205], v[96:99]
	v_mfma_f32_16x16x32_bf16 v[84:87], v[174:177], v[210:213], v[84:87]
	v_mfma_f32_16x16x32_bf16 v[80:83], v[182:185], v[210:213], v[80:83]
	v_mfma_f32_16x16x32_bf16 v[68:71], v[174:177], v[218:221], v[68:71]
	v_mfma_f32_16x16x32_bf16 v[64:67], v[182:185], v[218:221], v[64:67]
	s_barrier
	s_add_i32 s33, s60, s50
	v_lshl_add_u64 v[148:149], s[38:39], 0, v[130:131]
	s_mov_b32 m0, s33
	s_nop 0
	global_load_lds_dwordx4 v[148:149], off
	s_add_i32 m0, s33, 0x2000
	s_add_u32 s34, s38, 0x160000
	v_lshl_add_u64 v[190:191], s[38:39], 0, v[134:135]
	s_addc_u32 s35, s39, 0
	s_add_i32 s33, s61, s50
	global_load_lds_dwordx4 v[190:191], off
	v_lshl_add_u64 v[222:223], s[34:35], 0, v[130:131]
	s_mov_b32 m0, s33
	v_lshl_add_u64 v[224:225], s[40:41], 0, v[132:133]
	global_load_lds_dwordx4 v[222:223], off
	v_lshl_add_u64 v[222:223], s[34:35], 0, v[134:135]
	s_add_i32 m0, s33, 0x2000
	s_nop 0
	global_load_lds_dwordx4 v[222:223], off
	v_lshl_add_u64 v[222:223], s[40:41], 0, v[128:129]
	s_mov_b32 m0, s51
	s_nop 0
	global_load_lds_dwordx4 v[222:223], off
	s_mov_b32 m0, s54
	s_nop 0
	global_load_lds_dwordx4 v[224:225], off
	ds_read_b128 v[186:189], v155 offset:16384
	ds_read_b128 v[194:197], v155 offset:17408
	ds_read_b128 v[198:201], v155 offset:18432
	ds_read_b128 v[202:205], v155 offset:19456
	ds_read_b128 v[206:209], v155 offset:20480
	ds_read_b128 v[210:213], v155 offset:21504
	ds_read_b128 v[214:217], v155 offset:22528
	ds_read_b128 v[218:221], v155 offset:23552
	s_waitcnt vmcnt(8)
	s_waitcnt lgkmcnt(0)
	s_barrier
	s_waitcnt lgkmcnt(0)
	v_mfma_f32_16x16x32_bf16 v[60:63], v[144:147], v[186:189], v[60:63]
	v_mfma_f32_16x16x32_bf16 v[56:59], v[162:165], v[186:189], v[56:59]
	v_mfma_f32_16x16x32_bf16 v[44:47], v[144:147], v[198:201], v[44:47]
	v_mfma_f32_16x16x32_bf16 v[40:43], v[162:165], v[198:201], v[40:43]
	v_mfma_f32_16x16x32_bf16 v[28:31], v[144:147], v[206:209], v[28:31]
	v_mfma_f32_16x16x32_bf16 v[24:27], v[162:165], v[206:209], v[24:27]
	v_mfma_f32_16x16x32_bf16 v[12:15], v[144:147], v[214:217], v[12:15]
	v_mfma_f32_16x16x32_bf16 v[8:11], v[162:165], v[214:217], v[8:11]
	v_mfma_f32_16x16x32_bf16 v[60:63], v[158:161], v[194:197], v[60:63]
	v_mfma_f32_16x16x32_bf16 v[56:59], v[166:169], v[194:197], v[56:59]
	v_mfma_f32_16x16x32_bf16 v[44:47], v[158:161], v[202:205], v[44:47]
	v_mfma_f32_16x16x32_bf16 v[40:43], v[166:169], v[202:205], v[40:43]
	v_mfma_f32_16x16x32_bf16 v[28:31], v[158:161], v[210:213], v[28:31]
	v_mfma_f32_16x16x32_bf16 v[24:27], v[166:169], v[210:213], v[24:27]
	v_mfma_f32_16x16x32_bf16 v[12:15], v[158:161], v[218:221], v[12:15]
	v_mfma_f32_16x16x32_bf16 v[8:11], v[166:169], v[218:221], v[8:11]
	v_mfma_f32_16x16x32_bf16 v[52:55], v[170:173], v[186:189], v[52:55]
	v_mfma_f32_16x16x32_bf16 v[48:51], v[178:181], v[186:189], v[48:51]
	v_mfma_f32_16x16x32_bf16 v[36:39], v[170:173], v[198:201], v[36:39]
	v_mfma_f32_16x16x32_bf16 v[32:35], v[178:181], v[198:201], v[32:35]
	v_mfma_f32_16x16x32_bf16 v[20:23], v[170:173], v[206:209], v[20:23]
	v_mfma_f32_16x16x32_bf16 v[16:19], v[178:181], v[206:209], v[16:19]
	v_mfma_f32_16x16x32_bf16 v[4:7], v[170:173], v[214:217], v[4:7]
	v_mfma_f32_16x16x32_bf16 v[0:3], v[178:181], v[214:217], v[0:3]
	v_mfma_f32_16x16x32_bf16 v[52:55], v[174:177], v[194:197], v[52:55]
	v_mfma_f32_16x16x32_bf16 v[48:51], v[182:185], v[194:197], v[48:51]
	v_mfma_f32_16x16x32_bf16 v[36:39], v[174:177], v[202:205], v[36:39]
	v_mfma_f32_16x16x32_bf16 v[32:35], v[182:185], v[202:205], v[32:35]
	v_mfma_f32_16x16x32_bf16 v[20:23], v[174:177], v[210:213], v[20:23]
	v_mfma_f32_16x16x32_bf16 v[16:19], v[182:185], v[210:213], v[16:19]
	v_mfma_f32_16x16x32_bf16 v[4:7], v[174:177], v[218:221], v[4:7]
	v_mfma_f32_16x16x32_bf16 v[0:3], v[182:185], v[218:221], v[0:3]
	s_barrier
	s_add_i32 s33, 0, 0x18000
	s_add_i32 s69, 0, 0x1c000
	s_add_u32 s34, s40, 0x160000
	s_addc_u32 s35, s41, 0
	s_mov_b32 m0, s55
	v_lshl_add_u64 v[226:227], s[34:35], 0, v[128:129]
	global_load_lds_dwordx4 v[226:227], off
	v_lshl_add_u64 v[226:227], s[34:35], 0, v[132:133]
	s_mov_b32 m0, s56
	s_nop 0
	global_load_lds_dwordx4 v[226:227], off
	v_add_u32_e32 v157, s33, v151
	ds_read_b128 v[144:147], v157
	ds_read_b128 v[158:161], v157 offset:1024
	ds_read_b128 v[162:165], v157 offset:2048
	ds_read_b128 v[166:169], v157 offset:3072
	v_add_u32_e32 v157, s69, v151
	ds_read_b128 v[170:173], v157
	ds_read_b128 v[174:177], v157 offset:1024
	ds_read_b128 v[178:181], v157 offset:2048
	ds_read_b128 v[182:185], v157 offset:3072
	ds_read_b128 v[186:189], v155 offset:32768
	ds_read_b128 v[194:197], v155 offset:33792
	ds_read_b128 v[198:201], v155 offset:34816
	ds_read_b128 v[202:205], v155 offset:35840
	ds_read_b128 v[206:209], v155 offset:36864
	ds_read_b128 v[210:213], v155 offset:37888
	ds_read_b128 v[214:217], v155 offset:38912
	ds_read_b128 v[218:221], v155 offset:39936
	s_waitcnt vmcnt(8)
	s_waitcnt lgkmcnt(0)
	s_barrier
	s_waitcnt lgkmcnt(0)
	v_mfma_f32_16x16x32_bf16 v[124:127], v[144:147], v[186:189], v[124:127]
	v_mfma_f32_16x16x32_bf16 v[120:123], v[162:165], v[186:189], v[120:123]
	v_mfma_f32_16x16x32_bf16 v[108:111], v[144:147], v[198:201], v[108:111]
	v_mfma_f32_16x16x32_bf16 v[104:107], v[162:165], v[198:201], v[104:107]
	v_mfma_f32_16x16x32_bf16 v[92:95], v[144:147], v[206:209], v[92:95]
	v_mfma_f32_16x16x32_bf16 v[88:91], v[162:165], v[206:209], v[88:91]
	v_mfma_f32_16x16x32_bf16 v[76:79], v[144:147], v[214:217], v[76:79]
	v_mfma_f32_16x16x32_bf16 v[72:75], v[162:165], v[214:217], v[72:75]
	v_mfma_f32_16x16x32_bf16 v[124:127], v[158:161], v[194:197], v[124:127]
	v_mfma_f32_16x16x32_bf16 v[120:123], v[166:169], v[194:197], v[120:123]
	v_mfma_f32_16x16x32_bf16 v[108:111], v[158:161], v[202:205], v[108:111]
	v_mfma_f32_16x16x32_bf16 v[104:107], v[166:169], v[202:205], v[104:107]
	v_mfma_f32_16x16x32_bf16 v[92:95], v[158:161], v[210:213], v[92:95]
	v_mfma_f32_16x16x32_bf16 v[88:91], v[166:169], v[210:213], v[88:91]
	v_mfma_f32_16x16x32_bf16 v[76:79], v[158:161], v[218:221], v[76:79]
	v_mfma_f32_16x16x32_bf16 v[72:75], v[166:169], v[218:221], v[72:75]
	v_mfma_f32_16x16x32_bf16 v[116:119], v[170:173], v[186:189], v[116:119]
	v_mfma_f32_16x16x32_bf16 v[112:115], v[178:181], v[186:189], v[112:115]
	v_mfma_f32_16x16x32_bf16 v[100:103], v[170:173], v[198:201], v[100:103]
	v_mfma_f32_16x16x32_bf16 v[96:99], v[178:181], v[198:201], v[96:99]
	v_mfma_f32_16x16x32_bf16 v[84:87], v[170:173], v[206:209], v[84:87]
	v_mfma_f32_16x16x32_bf16 v[80:83], v[178:181], v[206:209], v[80:83]
	v_mfma_f32_16x16x32_bf16 v[68:71], v[170:173], v[214:217], v[68:71]
	v_mfma_f32_16x16x32_bf16 v[64:67], v[178:181], v[214:217], v[64:67]
	v_mfma_f32_16x16x32_bf16 v[116:119], v[174:177], v[194:197], v[116:119]
	v_mfma_f32_16x16x32_bf16 v[112:115], v[182:185], v[194:197], v[112:115]
	v_mfma_f32_16x16x32_bf16 v[100:103], v[174:177], v[202:205], v[100:103]
	v_mfma_f32_16x16x32_bf16 v[96:99], v[182:185], v[202:205], v[96:99]
	v_mfma_f32_16x16x32_bf16 v[84:87], v[174:177], v[210:213], v[84:87]
	v_mfma_f32_16x16x32_bf16 v[80:83], v[182:185], v[210:213], v[80:83]
	v_mfma_f32_16x16x32_bf16 v[68:71], v[174:177], v[218:221], v[68:71]
	v_mfma_f32_16x16x32_bf16 v[64:67], v[182:185], v[218:221], v[64:67]
	s_barrier
	s_add_i32 s33, s33, s50
	v_lshl_add_u64 v[148:149], v[148:149], 0, s[18:19]
	s_mov_b32 m0, s33
	s_nop 0
	global_load_lds_dwordx4 v[148:149], off
	s_add_i32 m0, s33, 0x2000
	s_add_u32 s34, s38, 0x160080
	v_lshl_add_u64 v[148:149], v[190:191], 0, s[18:19]
	s_addc_u32 s35, s39, 0
	s_add_i32 s33, s69, s50
	global_load_lds_dwordx4 v[148:149], off
	v_lshl_add_u64 v[148:149], s[34:35], 0, v[130:131]
	s_mov_b32 m0, s33
	s_nop 0
	global_load_lds_dwordx4 v[148:149], off
	v_lshl_add_u64 v[148:149], s[34:35], 0, v[134:135]
	s_add_i32 m0, s33, 0x2000
	s_nop 0
	global_load_lds_dwordx4 v[148:149], off
	v_lshl_add_u64 v[148:149], v[222:223], 0, s[18:19]
	s_mov_b32 m0, s58
	s_nop 0
	global_load_lds_dwordx4 v[148:149], off
	v_lshl_add_u64 v[148:149], v[224:225], 0, s[18:19]
	s_mov_b32 m0, s59
	s_nop 0
	global_load_lds_dwordx4 v[148:149], off
	ds_read_b128 v[186:189], v155 offset:49152
	ds_read_b128 v[194:197], v155 offset:50176
	ds_read_b128 v[198:201], v155 offset:51200
	ds_read_b128 v[202:205], v155 offset:52224
	ds_read_b128 v[206:209], v155 offset:53248
	ds_read_b128 v[210:213], v155 offset:54272
	ds_read_b128 v[214:217], v155 offset:55296
	ds_read_b128 v[218:221], v155 offset:56320
	s_waitcnt vmcnt(8)
	s_waitcnt lgkmcnt(0)
	s_barrier
	s_waitcnt lgkmcnt(0)
	v_mfma_f32_16x16x32_bf16 v[60:63], v[144:147], v[186:189], v[60:63]
	v_mfma_f32_16x16x32_bf16 v[56:59], v[162:165], v[186:189], v[56:59]
	v_mfma_f32_16x16x32_bf16 v[44:47], v[144:147], v[198:201], v[44:47]
	v_mfma_f32_16x16x32_bf16 v[40:43], v[162:165], v[198:201], v[40:43]
	v_mfma_f32_16x16x32_bf16 v[28:31], v[144:147], v[206:209], v[28:31]
	v_mfma_f32_16x16x32_bf16 v[24:27], v[162:165], v[206:209], v[24:27]
	v_mfma_f32_16x16x32_bf16 v[12:15], v[144:147], v[214:217], v[12:15]
	v_mfma_f32_16x16x32_bf16 v[8:11], v[162:165], v[214:217], v[8:11]
	v_mfma_f32_16x16x32_bf16 v[60:63], v[158:161], v[194:197], v[60:63]
	v_mfma_f32_16x16x32_bf16 v[56:59], v[166:169], v[194:197], v[56:59]
	v_mfma_f32_16x16x32_bf16 v[44:47], v[158:161], v[202:205], v[44:47]
	v_mfma_f32_16x16x32_bf16 v[40:43], v[166:169], v[202:205], v[40:43]
	v_mfma_f32_16x16x32_bf16 v[28:31], v[158:161], v[210:213], v[28:31]
	v_mfma_f32_16x16x32_bf16 v[24:27], v[166:169], v[210:213], v[24:27]
	v_mfma_f32_16x16x32_bf16 v[12:15], v[158:161], v[218:221], v[12:15]
	v_mfma_f32_16x16x32_bf16 v[8:11], v[166:169], v[218:221], v[8:11]
	v_mfma_f32_16x16x32_bf16 v[52:55], v[170:173], v[186:189], v[52:55]
	v_mfma_f32_16x16x32_bf16 v[48:51], v[178:181], v[186:189], v[48:51]
	v_mfma_f32_16x16x32_bf16 v[36:39], v[170:173], v[198:201], v[36:39]
	v_mfma_f32_16x16x32_bf16 v[32:35], v[178:181], v[198:201], v[32:35]
	v_mfma_f32_16x16x32_bf16 v[20:23], v[170:173], v[206:209], v[20:23]
	v_mfma_f32_16x16x32_bf16 v[16:19], v[178:181], v[206:209], v[16:19]
	v_mfma_f32_16x16x32_bf16 v[4:7], v[170:173], v[214:217], v[4:7]
	v_mfma_f32_16x16x32_bf16 v[0:3], v[178:181], v[214:217], v[0:3]
	v_mfma_f32_16x16x32_bf16 v[52:55], v[174:177], v[194:197], v[52:55]
	v_mfma_f32_16x16x32_bf16 v[48:51], v[182:185], v[194:197], v[48:51]
	v_mfma_f32_16x16x32_bf16 v[36:39], v[174:177], v[202:205], v[36:39]
	v_mfma_f32_16x16x32_bf16 v[32:35], v[182:185], v[202:205], v[32:35]
	v_mfma_f32_16x16x32_bf16 v[20:23], v[174:177], v[210:213], v[20:23]
	v_mfma_f32_16x16x32_bf16 v[16:19], v[182:185], v[210:213], v[16:19]
	v_mfma_f32_16x16x32_bf16 v[4:7], v[174:177], v[218:221], v[4:7]
	v_mfma_f32_16x16x32_bf16 v[0:3], v[182:185], v[218:221], v[0:3]
	s_barrier
	s_add_i32 s68, s68, 2
	s_add_u32 s66, s66, 0x100
	s_addc_u32 s67, s67, 0
	s_cmpk_gt_u32 s68, 0x55
	s_mov_b64 s[34:35], s[36:37]
	s_cbranch_scc0 .LBB0_2011
	s_and_b64 vcc, exec, s[20:21]
	s_cbranch_vccz .LBB0_2014
	s_barrier

.LBB0_2113:
	s_add_u32 s28, s24, s26
	s_addc_u32 s29, s25, s27
	s_add_u32 s28, s28, 0x100
	s_addc_u32 s29, s29, 0
	s_add_u32 s55, s21, s26
	s_addc_u32 s56, s53, s27
	s_cmpk_eq_i32 s26, 0x2b00
	s_cselect_b32 s31, s5, s29
	s_cselect_b32 s30, s4, s28
	s_cselect_b32 s29, s23, s56
	s_cselect_b32 s28, s22, s55
	v_lshl_add_u64 v[218:219], v[144:145], 0, s[26:27]
	s_add_i32 m0, s39, 0xc000
	s_nop 0
	global_load_lds_dwordx4 v[218:219], off
	v_lshl_add_u64 v[218:219], v[146:147], 0, s[26:27]
	s_add_i32 m0, s39, 0xe000
	s_nop 0
	global_load_lds_dwordx4 v[218:219], off
	v_add_u32_e32 v151, s48, v149
	ds_read_b128 v[152:155], v151
	ds_read_b128 v[156:159], v151 offset:1024
	ds_read_b128 v[160:163], v151 offset:2048
	ds_read_b128 v[164:167], v151 offset:3072
	v_add_u32_e32 v151, s49, v149
	ds_read_b128 v[168:171], v151
	ds_read_b128 v[172:175], v151 offset:1024
	ds_read_b128 v[176:179], v151 offset:2048
	ds_read_b128 v[180:183], v151 offset:3072
	ds_read_b128 v[184:187], v150
	ds_read_b128 v[188:191], v150 offset:1024
	ds_read_b128 v[194:197], v150 offset:2048
	ds_read_b128 v[198:201], v150 offset:3072
	ds_read_b128 v[202:205], v150 offset:4096
	ds_read_b128 v[206:209], v150 offset:5120
	ds_read_b128 v[210:213], v150 offset:6144
	ds_read_b128 v[214:217], v150 offset:7168
	s_waitcnt vmcnt(8)
	s_waitcnt lgkmcnt(0)
	s_barrier
	s_waitcnt lgkmcnt(0)
	v_mfma_f32_16x16x32_bf16 v[124:127], v[152:155], v[184:187], v[124:127]
	v_mfma_f32_16x16x32_bf16 v[120:123], v[160:163], v[184:187], v[120:123]
	v_mfma_f32_16x16x32_bf16 v[108:111], v[152:155], v[194:197], v[108:111]
	v_mfma_f32_16x16x32_bf16 v[104:107], v[160:163], v[194:197], v[104:107]
	v_mfma_f32_16x16x32_bf16 v[92:95], v[152:155], v[202:205], v[92:95]
	v_mfma_f32_16x16x32_bf16 v[88:91], v[160:163], v[202:205], v[88:91]
	v_mfma_f32_16x16x32_bf16 v[76:79], v[152:155], v[210:213], v[76:79]
	v_mfma_f32_16x16x32_bf16 v[72:75], v[160:163], v[210:213], v[72:75]
	v_mfma_f32_16x16x32_bf16 v[124:127], v[156:159], v[188:191], v[124:127]
	v_mfma_f32_16x16x32_bf16 v[120:123], v[164:167], v[188:191], v[120:123]
	v_mfma_f32_16x16x32_bf16 v[108:111], v[156:159], v[198:201], v[108:111]
	v_mfma_f32_16x16x32_bf16 v[104:107], v[164:167], v[198:201], v[104:107]
	v_mfma_f32_16x16x32_bf16 v[92:95], v[156:159], v[206:209], v[92:95]
	v_mfma_f32_16x16x32_bf16 v[88:91], v[164:167], v[206:209], v[88:91]
	v_mfma_f32_16x16x32_bf16 v[76:79], v[156:159], v[214:217], v[76:79]
	v_mfma_f32_16x16x32_bf16 v[72:75], v[164:167], v[214:217], v[72:75]
	v_mfma_f32_16x16x32_bf16 v[116:119], v[168:171], v[184:187], v[116:119]
	v_mfma_f32_16x16x32_bf16 v[112:115], v[176:179], v[184:187], v[112:115]
	v_mfma_f32_16x16x32_bf16 v[100:103], v[168:171], v[194:197], v[100:103]
	v_mfma_f32_16x16x32_bf16 v[96:99], v[176:179], v[194:197], v[96:99]
	v_mfma_f32_16x16x32_bf16 v[84:87], v[168:171], v[202:205], v[84:87]
	v_mfma_f32_16x16x32_bf16 v[80:83], v[176:179], v[202:205], v[80:83]
	v_mfma_f32_16x16x32_bf16 v[68:71], v[168:171], v[210:213], v[68:71]
	v_mfma_f32_16x16x32_bf16 v[64:67], v[176:179], v[210:213], v[64:67]
	v_mfma_f32_16x16x32_bf16 v[116:119], v[172:175], v[188:191], v[116:119]
	v_mfma_f32_16x16x32_bf16 v[112:115], v[180:183], v[188:191], v[112:115]
	v_mfma_f32_16x16x32_bf16 v[100:103], v[172:175], v[198:201], v[100:103]
	v_mfma_f32_16x16x32_bf16 v[96:99], v[180:183], v[198:201], v[96:99]
	v_mfma_f32_16x16x32_bf16 v[84:87], v[172:175], v[206:209], v[84:87]
	v_mfma_f32_16x16x32_bf16 v[80:83], v[180:183], v[206:209], v[80:83]
	v_mfma_f32_16x16x32_bf16 v[68:71], v[172:175], v[214:217], v[68:71]
	v_mfma_f32_16x16x32_bf16 v[64:67], v[180:183], v[214:217], v[64:67]
	s_barrier
	s_add_i32 s55, s48, s38
	v_lshl_add_u64 v[218:219], s[28:29], 0, v[130:131]
	s_mov_b32 m0, s55
	s_nop 0
	global_load_lds_dwordx4 v[218:219], off
	s_add_i32 m0, s55, 0x2000
	s_add_u32 s56, s28, 0x160000
	v_lshl_add_u64 v[220:221], s[28:29], 0, v[134:135]
	s_addc_u32 s57, s29, 0
	s_add_i32 s55, s49, s38
	global_load_lds_dwordx4 v[220:221], off
	v_lshl_add_u64 v[222:223], s[56:57], 0, v[130:131]
	s_mov_b32 m0, s55
	v_lshl_add_u64 v[224:225], s[30:31], 0, v[132:133]
	global_load_lds_dwordx4 v[222:223], off
	v_lshl_add_u64 v[222:223], s[56:57], 0, v[134:135]
	s_add_i32 m0, s55, 0x2000
	s_nop 0
	global_load_lds_dwordx4 v[222:223], off
	v_lshl_add_u64 v[222:223], s[30:31], 0, v[128:129]
	s_mov_b32 m0, s39
	s_nop 0
	global_load_lds_dwordx4 v[222:223], off
	s_mov_b32 m0, s40
	s_nop 0
	global_load_lds_dwordx4 v[224:225], off
	ds_read_b128 v[184:187], v150 offset:16384
	ds_read_b128 v[188:191], v150 offset:17408
	ds_read_b128 v[194:197], v150 offset:18432
	ds_read_b128 v[198:201], v150 offset:19456
	ds_read_b128 v[202:205], v150 offset:20480
	ds_read_b128 v[206:209], v150 offset:21504
	ds_read_b128 v[210:213], v150 offset:22528
	ds_read_b128 v[214:217], v150 offset:23552
	s_waitcnt vmcnt(8)
	s_waitcnt lgkmcnt(0)
	s_barrier
	s_waitcnt lgkmcnt(0)
	v_mfma_f32_16x16x32_bf16 v[60:63], v[152:155], v[184:187], v[60:63]
	v_mfma_f32_16x16x32_bf16 v[56:59], v[160:163], v[184:187], v[56:59]
	v_mfma_f32_16x16x32_bf16 v[44:47], v[152:155], v[194:197], v[44:47]
	v_mfma_f32_16x16x32_bf16 v[40:43], v[160:163], v[194:197], v[40:43]
	v_mfma_f32_16x16x32_bf16 v[28:31], v[152:155], v[202:205], v[28:31]
	v_mfma_f32_16x16x32_bf16 v[24:27], v[160:163], v[202:205], v[24:27]
	v_mfma_f32_16x16x32_bf16 v[12:15], v[152:155], v[210:213], v[12:15]
	v_mfma_f32_16x16x32_bf16 v[8:11], v[160:163], v[210:213], v[8:11]
	v_mfma_f32_16x16x32_bf16 v[60:63], v[156:159], v[188:191], v[60:63]
	v_mfma_f32_16x16x32_bf16 v[56:59], v[164:167], v[188:191], v[56:59]
	v_mfma_f32_16x16x32_bf16 v[44:47], v[156:159], v[198:201], v[44:47]
	v_mfma_f32_16x16x32_bf16 v[40:43], v[164:167], v[198:201], v[40:43]
	v_mfma_f32_16x16x32_bf16 v[28:31], v[156:159], v[206:209], v[28:31]
	v_mfma_f32_16x16x32_bf16 v[24:27], v[164:167], v[206:209], v[24:27]
	v_mfma_f32_16x16x32_bf16 v[12:15], v[156:159], v[214:217], v[12:15]
	v_mfma_f32_16x16x32_bf16 v[8:11], v[164:167], v[214:217], v[8:11]
	v_mfma_f32_16x16x32_bf16 v[52:55], v[168:171], v[184:187], v[52:55]
	v_mfma_f32_16x16x32_bf16 v[48:51], v[176:179], v[184:187], v[48:51]
	v_mfma_f32_16x16x32_bf16 v[36:39], v[168:171], v[194:197], v[36:39]
	v_mfma_f32_16x16x32_bf16 v[32:35], v[176:179], v[194:197], v[32:35]
	v_mfma_f32_16x16x32_bf16 v[20:23], v[168:171], v[202:205], v[20:23]
	v_mfma_f32_16x16x32_bf16 v[16:19], v[176:179], v[202:205], v[16:19]
	v_mfma_f32_16x16x32_bf16 v[4:7], v[168:171], v[210:213], v[4:7]
	v_mfma_f32_16x16x32_bf16 v[0:3], v[176:179], v[210:213], v[0:3]
	v_mfma_f32_16x16x32_bf16 v[52:55], v[172:175], v[188:191], v[52:55]
	v_mfma_f32_16x16x32_bf16 v[48:51], v[180:183], v[188:191], v[48:51]
	v_mfma_f32_16x16x32_bf16 v[36:39], v[172:175], v[198:201], v[36:39]
	v_mfma_f32_16x16x32_bf16 v[32:35], v[180:183], v[198:201], v[32:35]
	v_mfma_f32_16x16x32_bf16 v[20:23], v[172:175], v[206:209], v[20:23]
	v_mfma_f32_16x16x32_bf16 v[16:19], v[180:183], v[206:209], v[16:19]
	v_mfma_f32_16x16x32_bf16 v[4:7], v[172:175], v[214:217], v[4:7]
	v_mfma_f32_16x16x32_bf16 v[0:3], v[180:183], v[214:217], v[0:3]
	s_barrier
	s_add_i32 s55, 0, 0x18000
	s_add_i32 s56, 0, 0x1c000
	s_add_u32 s30, s30, 0x160000
	s_addc_u32 s31, s31, 0
	s_mov_b32 m0, s41
	v_lshl_add_u64 v[226:227], s[30:31], 0, v[128:129]
	global_load_lds_dwordx4 v[226:227], off
	v_lshl_add_u64 v[226:227], s[30:31], 0, v[132:133]
	s_mov_b32 m0, s42
	s_nop 0
	global_load_lds_dwordx4 v[226:227], off
	v_add_u32_e32 v151, s55, v149
	ds_read_b128 v[152:155], v151
	ds_read_b128 v[156:159], v151 offset:1024
	ds_read_b128 v[160:163], v151 offset:2048
	ds_read_b128 v[164:167], v151 offset:3072
	v_add_u32_e32 v151, s56, v149
	ds_read_b128 v[168:171], v151
	ds_read_b128 v[172:175], v151 offset:1024
	ds_read_b128 v[176:179], v151 offset:2048
	ds_read_b128 v[180:183], v151 offset:3072
	ds_read_b128 v[184:187], v150 offset:32768
	ds_read_b128 v[188:191], v150 offset:33792
	ds_read_b128 v[194:197], v150 offset:34816
	ds_read_b128 v[198:201], v150 offset:35840
	ds_read_b128 v[202:205], v150 offset:36864
	ds_read_b128 v[206:209], v150 offset:37888
	ds_read_b128 v[210:213], v150 offset:38912
	ds_read_b128 v[214:217], v150 offset:39936
	s_waitcnt vmcnt(8)
	s_waitcnt lgkmcnt(0)
	s_barrier
	s_waitcnt lgkmcnt(0)
	v_mfma_f32_16x16x32_bf16 v[124:127], v[152:155], v[184:187], v[124:127]
	v_mfma_f32_16x16x32_bf16 v[120:123], v[160:163], v[184:187], v[120:123]
	v_mfma_f32_16x16x32_bf16 v[108:111], v[152:155], v[194:197], v[108:111]
	v_mfma_f32_16x16x32_bf16 v[104:107], v[160:163], v[194:197], v[104:107]
	v_mfma_f32_16x16x32_bf16 v[92:95], v[152:155], v[202:205], v[92:95]
	v_mfma_f32_16x16x32_bf16 v[88:91], v[160:163], v[202:205], v[88:91]
	v_mfma_f32_16x16x32_bf16 v[76:79], v[152:155], v[210:213], v[76:79]
	v_mfma_f32_16x16x32_bf16 v[72:75], v[160:163], v[210:213], v[72:75]
	v_mfma_f32_16x16x32_bf16 v[124:127], v[156:159], v[188:191], v[124:127]
	v_mfma_f32_16x16x32_bf16 v[120:123], v[164:167], v[188:191], v[120:123]
	v_mfma_f32_16x16x32_bf16 v[108:111], v[156:159], v[198:201], v[108:111]
	v_mfma_f32_16x16x32_bf16 v[104:107], v[164:167], v[198:201], v[104:107]
	v_mfma_f32_16x16x32_bf16 v[92:95], v[156:159], v[206:209], v[92:95]
	v_mfma_f32_16x16x32_bf16 v[88:91], v[164:167], v[206:209], v[88:91]
	v_mfma_f32_16x16x32_bf16 v[76:79], v[156:159], v[214:217], v[76:79]
	v_mfma_f32_16x16x32_bf16 v[72:75], v[164:167], v[214:217], v[72:75]
	v_mfma_f32_16x16x32_bf16 v[116:119], v[168:171], v[184:187], v[116:119]
	v_mfma_f32_16x16x32_bf16 v[112:115], v[176:179], v[184:187], v[112:115]
	v_mfma_f32_16x16x32_bf16 v[100:103], v[168:171], v[194:197], v[100:103]
	v_mfma_f32_16x16x32_bf16 v[96:99], v[176:179], v[194:197], v[96:99]
	v_mfma_f32_16x16x32_bf16 v[84:87], v[168:171], v[202:205], v[84:87]
	v_mfma_f32_16x16x32_bf16 v[80:83], v[176:179], v[202:205], v[80:83]
	v_mfma_f32_16x16x32_bf16 v[68:71], v[168:171], v[210:213], v[68:71]
	v_mfma_f32_16x16x32_bf16 v[64:67], v[176:179], v[210:213], v[64:67]
	v_mfma_f32_16x16x32_bf16 v[116:119], v[172:175], v[188:191], v[116:119]
	v_mfma_f32_16x16x32_bf16 v[112:115], v[180:183], v[188:191], v[112:115]
	v_mfma_f32_16x16x32_bf16 v[100:103], v[172:175], v[198:201], v[100:103]
	v_mfma_f32_16x16x32_bf16 v[96:99], v[180:183], v[198:201], v[96:99]
	v_mfma_f32_16x16x32_bf16 v[84:87], v[172:175], v[206:209], v[84:87]
	v_mfma_f32_16x16x32_bf16 v[80:83], v[180:183], v[206:209], v[80:83]
	v_mfma_f32_16x16x32_bf16 v[68:71], v[172:175], v[214:217], v[68:71]
	v_mfma_f32_16x16x32_bf16 v[64:67], v[180:183], v[214:217], v[64:67]
	s_barrier
	s_add_i32 s30, s55, s38
	v_lshl_add_u64 v[218:219], v[218:219], 0, s[16:17]
	s_mov_b32 m0, s30
	s_nop 0
	global_load_lds_dwordx4 v[218:219], off
	s_add_i32 m0, s30, 0x2000
	s_add_u32 s28, s28, 0x160080
	v_lshl_add_u64 v[218:219], v[220:221], 0, s[16:17]
	s_addc_u32 s29, s29, 0
	s_add_i32 s30, s56, s38
	global_load_lds_dwordx4 v[218:219], off
	v_lshl_add_u64 v[218:219], s[28:29], 0, v[130:131]
	s_mov_b32 m0, s30
	s_nop 0
	global_load_lds_dwordx4 v[218:219], off
	v_lshl_add_u64 v[218:219], s[28:29], 0, v[134:135]
	s_add_i32 m0, s30, 0x2000
	s_nop 0
	global_load_lds_dwordx4 v[218:219], off
	v_lshl_add_u64 v[218:219], v[222:223], 0, s[16:17]
	s_mov_b32 m0, s45
	s_nop 0
	global_load_lds_dwordx4 v[218:219], off
	v_lshl_add_u64 v[218:219], v[224:225], 0, s[16:17]
	s_mov_b32 m0, s46
	s_nop 0
	global_load_lds_dwordx4 v[218:219], off
	ds_read_b128 v[184:187], v150 offset:49152
	ds_read_b128 v[188:191], v150 offset:50176
	ds_read_b128 v[194:197], v150 offset:51200
	ds_read_b128 v[198:201], v150 offset:52224
	ds_read_b128 v[202:205], v150 offset:53248
	ds_read_b128 v[206:209], v150 offset:54272
	ds_read_b128 v[210:213], v150 offset:55296
	ds_read_b128 v[214:217], v150 offset:56320
	s_waitcnt vmcnt(8)
	s_waitcnt lgkmcnt(0)
	s_barrier
	s_waitcnt lgkmcnt(0)
	v_mfma_f32_16x16x32_bf16 v[60:63], v[152:155], v[184:187], v[60:63]
	v_mfma_f32_16x16x32_bf16 v[56:59], v[160:163], v[184:187], v[56:59]
	v_mfma_f32_16x16x32_bf16 v[44:47], v[152:155], v[194:197], v[44:47]
	v_mfma_f32_16x16x32_bf16 v[40:43], v[160:163], v[194:197], v[40:43]
	v_mfma_f32_16x16x32_bf16 v[28:31], v[152:155], v[202:205], v[28:31]
	v_mfma_f32_16x16x32_bf16 v[24:27], v[160:163], v[202:205], v[24:27]
	v_mfma_f32_16x16x32_bf16 v[12:15], v[152:155], v[210:213], v[12:15]
	v_mfma_f32_16x16x32_bf16 v[8:11], v[160:163], v[210:213], v[8:11]
	v_mfma_f32_16x16x32_bf16 v[60:63], v[156:159], v[188:191], v[60:63]
	v_mfma_f32_16x16x32_bf16 v[56:59], v[164:167], v[188:191], v[56:59]
	v_mfma_f32_16x16x32_bf16 v[44:47], v[156:159], v[198:201], v[44:47]
	v_mfma_f32_16x16x32_bf16 v[40:43], v[164:167], v[198:201], v[40:43]
	v_mfma_f32_16x16x32_bf16 v[28:31], v[156:159], v[206:209], v[28:31]
	v_mfma_f32_16x16x32_bf16 v[24:27], v[164:167], v[206:209], v[24:27]
	v_mfma_f32_16x16x32_bf16 v[12:15], v[156:159], v[214:217], v[12:15]
	v_mfma_f32_16x16x32_bf16 v[8:11], v[164:167], v[214:217], v[8:11]
	v_mfma_f32_16x16x32_bf16 v[52:55], v[168:171], v[184:187], v[52:55]
	v_mfma_f32_16x16x32_bf16 v[48:51], v[176:179], v[184:187], v[48:51]
	v_mfma_f32_16x16x32_bf16 v[36:39], v[168:171], v[194:197], v[36:39]
	v_mfma_f32_16x16x32_bf16 v[32:35], v[176:179], v[194:197], v[32:35]
	v_mfma_f32_16x16x32_bf16 v[20:23], v[168:171], v[202:205], v[20:23]
	v_mfma_f32_16x16x32_bf16 v[16:19], v[176:179], v[202:205], v[16:19]
	v_mfma_f32_16x16x32_bf16 v[4:7], v[168:171], v[210:213], v[4:7]
	v_mfma_f32_16x16x32_bf16 v[0:3], v[176:179], v[210:213], v[0:3]
	v_mfma_f32_16x16x32_bf16 v[52:55], v[172:175], v[188:191], v[52:55]
	v_mfma_f32_16x16x32_bf16 v[48:51], v[180:183], v[188:191], v[48:51]
	v_mfma_f32_16x16x32_bf16 v[36:39], v[172:175], v[198:201], v[36:39]
	v_mfma_f32_16x16x32_bf16 v[32:35], v[180:183], v[198:201], v[32:35]
	v_mfma_f32_16x16x32_bf16 v[20:23], v[172:175], v[206:209], v[20:23]
	v_mfma_f32_16x16x32_bf16 v[16:19], v[180:183], v[206:209], v[16:19]
	v_mfma_f32_16x16x32_bf16 v[4:7], v[172:175], v[214:217], v[4:7]
	v_mfma_f32_16x16x32_bf16 v[0:3], v[180:183], v[214:217], v[0:3]
	s_barrier
	s_add_i32 s54, s54, 2
	s_add_u32 s26, s26, 0x100
	s_addc_u32 s27, s27, 0
	s_cmpk_gt_u32 s54, 0x55
	s_cbranch_scc0 .LBB0_2113
	s_and_b64 vcc, exec, s[18:19]
	s_cbranch_vccz .LBB0_2116
	s_barrier
